# merged the vmcnt(8) and lgkmcnt(0) waits of each K-loop load segment into one s_waitcnt
# speedup vs baseline: 1.0016x; 1.0016x over previous
; #define PG8_STAGE(bufoff, gbase, voff) do { _Pragma("unroll") for (int _i = 0; _i < 2; ++_i) \
;         __builtin_amdgcn_global_load_lds((const unsigned*)((const char*)(gbase) + (voff)[_i]), (LAS unsigned*)(lds + (bufoff) + ldsw + _i * 8192), 16, 0, 0); } while (0)
; #define PG8_LDA(dst, b, h) do { _Pragma("unroll") for (int m = 0; m < 4; ++m) _Pragma("unroll") for (int k = 0; k < 2; ++k) dst[m][k] = *(const LAS bf16x8*)(lds + PG8_SA(b, h) + aoff + m * 2048 + k * 1024); } while (0)
; #define PG8_LDB(dst, b, h) do { _Pragma("unroll") for (int n = 0; n < 2; ++n) _Pragma("unroll") for (int k = 0; k < 2; ++k) dst[n][k] = *(const LAS bf16x8*)(lds + PG8_SB(b, h) + boff + n * 2048 + k * 1024); } while (0)
; #define PG8_MMA(ai, bj, At, Bt) do { __builtin_amdgcn_s_setprio(1); _Pragma("unroll") for (int m = 0; m < 4; ++m) _Pragma("unroll") for (int n = 0; n < 2; ++n) _Pragma("unroll") for (int k = 0; k < 2; ++k) \
;         acc[ai][bj][m][n] = __builtin_amdgcn_mfma_f32_16x16x32_bf16(Bt[n][k], At[m][k], acc[ai][bj][m][n], 0, 0, 0); __builtin_amdgcn_s_setprio(0); } while (0)
; #define PG8_WAIT_V(n) asm volatile("s_waitcnt vmcnt(" #n ")" ::: "memory")
; #define PG8_WAIT_L(n) asm volatile("s_waitcnt lgkmcnt(" #n ")" ::: "memory")
; #define PG8_BAR __builtin_amdgcn_s_barrier()
; #define PG8_SCHED __builtin_amdgcn_sched_barrier(0)
; template <class Epi, bool ALIGN_EPI>
; __device__ __forceinline__ void gemm_phase(LAS unsigned char* lds, const Gemm g, const StaticOrder& S, const Epi& E, const int tid) {
;     ...
;         for (int t = 0; t < nt; t += 2) {
;             const bool last = (t == nt - 2);
;             const char* a1 = cA + (size_t)(t + 1) * kstepA;
;             const char* a2 = last ? nA : cA + (size_t)(t + 2) * kstepA; const char* b2 = last ? nB : cB + (size_t)(t + 2) * kstepB;
;             const char* a3 = a2 + kstepA; const char* b3 = b2 + kstepB;
;             PG8_LDB(B0, 0, 0); PG8_LDB(B1, 0, 1); PG8_SCHED; PG8_LDA(At, 0, 0); PG8_STAGE(PG8_SA(1, 1), a1 + hstepA, voffA);
;             PG8_WAIT_V(8); PG8_WAIT_L(0); PG8_BAR; PG8_MMA(0, 0, At, B0); PG8_MMA(0, 1, At, B1); PG8_BAR; PG8_SCHED;
.LBB0_211:
	s_add_u32 s50, s48, 0x4000
	s_addc_u32 s51, s49, 0
	s_cmp_eq_u32 s89, 28
	s_cselect_b32 s54, s87, s50
	s_cselect_b32 s55, s43, s51
	s_cselect_b32 s52, vcc_lo, vcc_hi
	s_cselect_b32 s53, s35, s88
	s_add_u32 s50, s54, 0x8000
	s_addc_u32 s51, s55, 0
	s_add_i32 s90, 0, 0x10000
	v_add_u32_e32 v0, s90, v160
	s_add_i32 s92, 0, 0x14000
	ds_read_b128 v[132:135], v0
	ds_read_b128 v[136:139], v0 offset:1024
	ds_read_b128 v[152:155], v0 offset:2048
	ds_read_b128 v[156:159], v0 offset:3072
	v_add_u32_e32 v0, s92, v160
	ds_read_b128 v[162:165], v0
	ds_read_b128 v[166:169], v0 offset:1024
	ds_read_b128 v[170:173], v0 offset:2048
	ds_read_b128 v[174:177], v0 offset:3072
	s_add_i32 m0, s72, 0xc000
	ds_read_b128 v[178:181], v161
	ds_read_b128 v[182:185], v161 offset:1024
	ds_read_b128 v[186:189], v161 offset:2048
	ds_read_b128 v[190:193], v161 offset:3072
	ds_read_b128 v[194:197], v161 offset:4096
	ds_read_b128 v[198:201], v161 offset:5120
	ds_read_b128 v[214:217], v161 offset:6144
	ds_read_b128 v[218:221], v161 offset:7168
	global_load_lds_dwordx4 v148, s[48:49]
	s_add_i32 m0, s72, 0xe000
	s_nop 0
	global_load_lds_dwordx4 v150, s[48:49]
	s_waitcnt vmcnt(8) lgkmcnt(0)
	s_barrier


; #define PG8_MMA(ai, bj, At, Bt) do { __builtin_amdgcn_s_setprio(1); _Pragma("unroll") for (int m = 0; m < 4; ++m) _Pragma("unroll") for (int n = 0; n < 2; ++n) _Pragma("unroll") for (int k = 0; k < 2; ++k) \
;         acc[ai][bj][m][n] = __builtin_amdgcn_mfma_f32_16x16x32_bf16(Bt[n][k], At[m][k], acc[ai][bj][m][n], 0, 0, 0); __builtin_amdgcn_s_setprio(0); } while (0)
; #define PG8_WAIT_V(n) asm volatile("s_waitcnt vmcnt(" #n ")" ::: "memory")
; #define PG8_WAIT_L(n) asm volatile("s_waitcnt lgkmcnt(" #n ")" ::: "memory")
; #define PG8_BAR __builtin_amdgcn_s_barrier()
; #define PG8_SCHED __builtin_amdgcn_sched_barrier(0)
; template <class Epi, bool ALIGN_EPI>
; __device__ __forceinline__ void gemm_phase(LAS unsigned char* lds, const Gemm g, const StaticOrder& S, const Epi& E, const int tid) {
;     ...
;             PG8_WAIT_V(8); PG8_WAIT_L(0); PG8_BAR; PG8_MMA(0, 0, At, B0); PG8_MMA(0, 1, At, B1); PG8_BAR; PG8_SCHED;
	v_mfma_f32_16x16x32_bf16 v[88:91], v[132:135], v[178:181], v[88:91]
	v_mfma_f32_16x16x32_bf16 v[124:127], v[152:155], v[178:181], v[124:127]
	v_mfma_f32_16x16x32_bf16 v[52:55], v[132:135], v[186:189], v[52:55]
	v_mfma_f32_16x16x32_bf16 v[120:123], v[152:155], v[186:189], v[120:123]
	v_mfma_f32_16x16x32_bf16 v[40:43], v[132:135], v[194:197], v[40:43]
	v_mfma_f32_16x16x32_bf16 v[116:119], v[152:155], v[194:197], v[116:119]
	v_mfma_f32_16x16x32_bf16 v[36:39], v[132:135], v[214:217], v[36:39]
	v_mfma_f32_16x16x32_bf16 v[112:115], v[152:155], v[214:217], v[112:115]
	v_mfma_f32_16x16x32_bf16 v[88:91], v[136:139], v[182:185], v[88:91]
	v_mfma_f32_16x16x32_bf16 v[124:127], v[156:159], v[182:185], v[124:127]
	v_mfma_f32_16x16x32_bf16 v[52:55], v[136:139], v[190:193], v[52:55]
	v_mfma_f32_16x16x32_bf16 v[120:123], v[156:159], v[190:193], v[120:123]
	v_mfma_f32_16x16x32_bf16 v[40:43], v[136:139], v[198:201], v[40:43]
	v_mfma_f32_16x16x32_bf16 v[116:119], v[156:159], v[198:201], v[116:119]
	v_mfma_f32_16x16x32_bf16 v[36:39], v[136:139], v[218:221], v[36:39]
	v_mfma_f32_16x16x32_bf16 v[112:115], v[156:159], v[218:221], v[112:115]


; #define PG8_MMA(ai, bj, At, Bt) do { __builtin_amdgcn_s_setprio(1); _Pragma("unroll") for (int m = 0; m < 4; ++m) _Pragma("unroll") for (int n = 0; n < 2; ++n) _Pragma("unroll") for (int k = 0; k < 2; ++k) \
;         acc[ai][bj][m][n] = __builtin_amdgcn_mfma_f32_16x16x32_bf16(Bt[n][k], At[m][k], acc[ai][bj][m][n], 0, 0, 0); __builtin_amdgcn_s_setprio(0); } while (0)
; #define PG8_WAIT_V(n) asm volatile("s_waitcnt vmcnt(" #n ")" ::: "memory")
; #define PG8_WAIT_L(n) asm volatile("s_waitcnt lgkmcnt(" #n ")" ::: "memory")
; #define PG8_BAR __builtin_amdgcn_s_barrier()
; #define PG8_SCHED __builtin_amdgcn_sched_barrier(0)
; template <class Epi, bool ALIGN_EPI>
; __device__ __forceinline__ void gemm_phase(LAS unsigned char* lds, const Gemm g, const StaticOrder& S, const Epi& E, const int tid) {
;     ...
;             PG8_WAIT_V(8); PG8_WAIT_L(0); PG8_BAR; PG8_MMA(0, 0, At, B0); PG8_MMA(0, 1, At, B1); PG8_BAR; PG8_SCHED;
	v_mfma_f32_16x16x32_bf16 v[80:83], v[162:165], v[178:181], v[80:83]
	v_mfma_f32_16x16x32_bf16 v[128:131], v[170:173], v[178:181], v[128:131]
	v_mfma_f32_16x16x32_bf16 v[68:71], v[162:165], v[186:189], v[68:71]
	v_mfma_f32_16x16x32_bf16 v[108:111], v[170:173], v[186:189], v[108:111]
	v_mfma_f32_16x16x32_bf16 v[60:63], v[162:165], v[194:197], v[60:63]
	v_mfma_f32_16x16x32_bf16 v[104:107], v[170:173], v[194:197], v[104:107]
	v_mfma_f32_16x16x32_bf16 v[48:51], v[162:165], v[214:217], v[48:51]
	v_mfma_f32_16x16x32_bf16 v[100:103], v[170:173], v[214:217], v[100:103]
	v_mfma_f32_16x16x32_bf16 v[80:83], v[166:169], v[182:185], v[80:83]
	v_mfma_f32_16x16x32_bf16 v[128:131], v[174:177], v[182:185], v[128:131]
	v_mfma_f32_16x16x32_bf16 v[68:71], v[166:169], v[190:193], v[68:71]
	v_mfma_f32_16x16x32_bf16 v[108:111], v[174:177], v[190:193], v[108:111]
	v_mfma_f32_16x16x32_bf16 v[60:63], v[166:169], v[198:201], v[60:63]
	v_mfma_f32_16x16x32_bf16 v[104:107], v[174:177], v[198:201], v[104:107]
	v_mfma_f32_16x16x32_bf16 v[48:51], v[166:169], v[218:221], v[48:51]
	v_mfma_f32_16x16x32_bf16 v[100:103], v[174:177], v[218:221], v[100:103]

; #define PG8_STAGE(bufoff, gbase, voff) do { _Pragma("unroll") for (int _i = 0; _i < 2; ++_i) \
;         __builtin_amdgcn_global_load_lds((const unsigned*)((const char*)(gbase) + (voff)[_i]), (LAS unsigned*)(lds + (bufoff) + ldsw + _i * 8192), 16, 0, 0); } while (0)
; #define PG8_LDA(dst, b, h) do { _Pragma("unroll") for (int m = 0; m < 4; ++m) _Pragma("unroll") for (int k = 0; k < 2; ++k) dst[m][k] = *(const LAS bf16x8*)(lds + PG8_SA(b, h) + aoff + m * 2048 + k * 1024); } while (0)
; #define PG8_MMA(ai, bj, At, Bt) do { __builtin_amdgcn_s_setprio(1); _Pragma("unroll") for (int m = 0; m < 4; ++m) _Pragma("unroll") for (int n = 0; n < 2; ++n) _Pragma("unroll") for (int k = 0; k < 2; ++k) \
;         acc[ai][bj][m][n] = __builtin_amdgcn_mfma_f32_16x16x32_bf16(Bt[n][k], At[m][k], acc[ai][bj][m][n], 0, 0, 0); __builtin_amdgcn_s_setprio(0); } while (0)
; #define PG8_WAIT_V(n) asm volatile("s_waitcnt vmcnt(" #n ")" ::: "memory")
; #define PG8_WAIT_L(n) asm volatile("s_waitcnt lgkmcnt(" #n ")" ::: "memory")
; #define PG8_BAR __builtin_amdgcn_s_barrier()
; #define PG8_SCHED __builtin_amdgcn_sched_barrier(0)
; template <class Epi, bool ALIGN_EPI>
; __device__ __forceinline__ void gemm_phase(LAS unsigned char* lds, const Gemm g, const StaticOrder& S, const Epi& E, const int tid) {
;     ...
;             PG8_WAIT_V(8); PG8_WAIT_L(0); PG8_BAR; PG8_MMA(0, 0, At, B0); PG8_MMA(0, 1, At, B1); PG8_BAR; PG8_SCHED;
;             PG8_LDA(At, 0, 1); PG8_STAGE(PG8_SB(0, 0), b2, voffB); PG8_STAGE(PG8_SB(0, 1), b2 + hstepB, voffB); PG8_STAGE(PG8_SA(0, 0), a2, voffA);
;             PG8_WAIT_V(8); PG8_WAIT_L(0); PG8_BAR; PG8_MMA(1, 0, At, B0); PG8_MMA(1, 1, At, B1); PG8_BAR; PG8_SCHED;
	s_barrier
	s_add_i32 s90, s90, s71
	s_mov_b32 m0, s90
	ds_read_b128 v[178:181], v161 offset:16384
	ds_read_b128 v[182:185], v161 offset:17408
	ds_read_b128 v[186:189], v161 offset:18432
	ds_read_b128 v[190:193], v161 offset:19456
	ds_read_b128 v[194:197], v161 offset:20480
	ds_read_b128 v[198:201], v161 offset:21504
	ds_read_b128 v[214:217], v161 offset:22528
	ds_read_b128 v[218:221], v161 offset:23552
	global_load_lds_dwordx4 v144, s[52:53]
	s_add_i32 m0, s90, 0x2000
	s_add_u32 s90, s52, 0x4000
	s_addc_u32 s91, s53, 0
	s_add_i32 s92, s92, s71
	global_load_lds_dwordx4 v140, s[52:53]
	s_mov_b32 m0, s92
	s_nop 0
	global_load_lds_dwordx4 v144, s[90:91]
	s_add_i32 m0, s92, 0x2000
	s_nop 0
	global_load_lds_dwordx4 v140, s[90:91]
	s_mov_b32 m0, s72
	s_nop 0
	global_load_lds_dwordx4 v146, s[54:55]
	s_mov_b32 m0, s73
	s_nop 0
	global_load_lds_dwordx4 v142, s[54:55]
	s_waitcnt vmcnt(8) lgkmcnt(0)
	s_barrier


; #define PG8_MMA(ai, bj, At, Bt) do { __builtin_amdgcn_s_setprio(1); _Pragma("unroll") for (int m = 0; m < 4; ++m) _Pragma("unroll") for (int n = 0; n < 2; ++n) _Pragma("unroll") for (int k = 0; k < 2; ++k) \
;         acc[ai][bj][m][n] = __builtin_amdgcn_mfma_f32_16x16x32_bf16(Bt[n][k], At[m][k], acc[ai][bj][m][n], 0, 0, 0); __builtin_amdgcn_s_setprio(0); } while (0)
; #define PG8_WAIT_V(n) asm volatile("s_waitcnt vmcnt(" #n ")" ::: "memory")
; #define PG8_WAIT_L(n) asm volatile("s_waitcnt lgkmcnt(" #n ")" ::: "memory")
; #define PG8_BAR __builtin_amdgcn_s_barrier()
; #define PG8_SCHED __builtin_amdgcn_sched_barrier(0)
; template <class Epi, bool ALIGN_EPI>
; __device__ __forceinline__ void gemm_phase(LAS unsigned char* lds, const Gemm g, const StaticOrder& S, const Epi& E, const int tid) {
;     ...
;             PG8_WAIT_V(8); PG8_WAIT_L(0); PG8_BAR; PG8_MMA(1, 0, At, B0); PG8_MMA(1, 1, At, B1); PG8_BAR; PG8_SCHED;
	v_mfma_f32_16x16x32_bf16 v[24:27], v[132:135], v[178:181], v[24:27]
	v_mfma_f32_16x16x32_bf16 v[92:95], v[152:155], v[178:181], v[92:95]
	v_mfma_f32_16x16x32_bf16 v[16:19], v[132:135], v[186:189], v[16:19]
	v_mfma_f32_16x16x32_bf16 v[84:87], v[152:155], v[186:189], v[84:87]
	v_mfma_f32_16x16x32_bf16 v[8:11], v[132:135], v[194:197], v[8:11]
	v_mfma_f32_16x16x32_bf16 v[76:79], v[152:155], v[194:197], v[76:79]
	v_mfma_f32_16x16x32_bf16 v[2:5], v[132:135], v[214:217], v[4:7]
	v_mfma_f32_16x16x32_bf16 v[64:67], v[152:155], v[214:217], v[64:67]
	v_mfma_f32_16x16x32_bf16 v[24:27], v[136:139], v[182:185], v[24:27]
	v_mfma_f32_16x16x32_bf16 v[92:95], v[156:159], v[182:185], v[92:95]
	v_mfma_f32_16x16x32_bf16 v[16:19], v[136:139], v[190:193], v[16:19]
	v_mfma_f32_16x16x32_bf16 v[84:87], v[156:159], v[190:193], v[84:87]
	v_mfma_f32_16x16x32_bf16 v[8:11], v[136:139], v[198:201], v[8:11]
	v_mfma_f32_16x16x32_bf16 v[76:79], v[156:159], v[198:201], v[76:79]
	v_mfma_f32_16x16x32_bf16 v[2:5], v[136:139], v[218:221], v[2:5]
	v_mfma_f32_16x16x32_bf16 v[64:67], v[156:159], v[218:221], v[64:67]


; #define PG8_MMA(ai, bj, At, Bt) do { __builtin_amdgcn_s_setprio(1); _Pragma("unroll") for (int m = 0; m < 4; ++m) _Pragma("unroll") for (int n = 0; n < 2; ++n) _Pragma("unroll") for (int k = 0; k < 2; ++k) \
;         acc[ai][bj][m][n] = __builtin_amdgcn_mfma_f32_16x16x32_bf16(Bt[n][k], At[m][k], acc[ai][bj][m][n], 0, 0, 0); __builtin_amdgcn_s_setprio(0); } while (0)
; #define PG8_WAIT_V(n) asm volatile("s_waitcnt vmcnt(" #n ")" ::: "memory")
; #define PG8_WAIT_L(n) asm volatile("s_waitcnt lgkmcnt(" #n ")" ::: "memory")
; #define PG8_BAR __builtin_amdgcn_s_barrier()
; #define PG8_SCHED __builtin_amdgcn_sched_barrier(0)
; template <class Epi, bool ALIGN_EPI>
; __device__ __forceinline__ void gemm_phase(LAS unsigned char* lds, const Gemm g, const StaticOrder& S, const Epi& E, const int tid) {
;     ...
;             PG8_WAIT_V(8); PG8_WAIT_L(0); PG8_BAR; PG8_MMA(1, 0, At, B0); PG8_MMA(1, 1, At, B1); PG8_BAR; PG8_SCHED;
	v_mfma_f32_16x16x32_bf16 v[32:35], v[162:165], v[178:181], v[32:35]
	v_mfma_f32_16x16x32_bf16 v[72:75], v[170:173], v[178:181], v[72:75]
	v_mfma_f32_16x16x32_bf16 v[28:31], v[162:165], v[186:189], v[28:31]
	v_mfma_f32_16x16x32_bf16 v[96:99], v[170:173], v[186:189], v[96:99]
	v_mfma_f32_16x16x32_bf16 v[20:23], v[162:165], v[194:197], v[20:23]
	v_mfma_f32_16x16x32_bf16 v[56:59], v[170:173], v[194:197], v[56:59]
	v_mfma_f32_16x16x32_bf16 v[12:15], v[162:165], v[214:217], v[12:15]
	v_mfma_f32_16x16x32_bf16 v[44:47], v[170:173], v[214:217], v[44:47]
	v_mfma_f32_16x16x32_bf16 v[32:35], v[166:169], v[182:185], v[32:35]
	v_mfma_f32_16x16x32_bf16 v[72:75], v[174:177], v[182:185], v[72:75]
	v_mfma_f32_16x16x32_bf16 v[28:31], v[166:169], v[190:193], v[28:31]
	v_mfma_f32_16x16x32_bf16 v[96:99], v[174:177], v[190:193], v[96:99]
	v_mfma_f32_16x16x32_bf16 v[20:23], v[166:169], v[198:201], v[20:23]
	v_mfma_f32_16x16x32_bf16 v[56:59], v[174:177], v[198:201], v[56:59]
	v_mfma_f32_16x16x32_bf16 v[12:15], v[166:169], v[218:221], v[12:15]
	v_mfma_f32_16x16x32_bf16 v[44:47], v[174:177], v[218:221], v[44:47]

; #define PG8_STAGE(bufoff, gbase, voff) do { _Pragma("unroll") for (int _i = 0; _i < 2; ++_i) \
;         __builtin_amdgcn_global_load_lds((const unsigned*)((const char*)(gbase) + (voff)[_i]), (LAS unsigned*)(lds + (bufoff) + ldsw + _i * 8192), 16, 0, 0); } while (0)
; #define PG8_LDA(dst, b, h) do { _Pragma("unroll") for (int m = 0; m < 4; ++m) _Pragma("unroll") for (int k = 0; k < 2; ++k) dst[m][k] = *(const LAS bf16x8*)(lds + PG8_SA(b, h) + aoff + m * 2048 + k * 1024); } while (0)
; #define PG8_LDB(dst, b, h) do { _Pragma("unroll") for (int n = 0; n < 2; ++n) _Pragma("unroll") for (int k = 0; k < 2; ++k) dst[n][k] = *(const LAS bf16x8*)(lds + PG8_SB(b, h) + boff + n * 2048 + k * 1024); } while (0)
; #define PG8_MMA(ai, bj, At, Bt) do { __builtin_amdgcn_s_setprio(1); _Pragma("unroll") for (int m = 0; m < 4; ++m) _Pragma("unroll") for (int n = 0; n < 2; ++n) _Pragma("unroll") for (int k = 0; k < 2; ++k) \
;         acc[ai][bj][m][n] = __builtin_amdgcn_mfma_f32_16x16x32_bf16(Bt[n][k], At[m][k], acc[ai][bj][m][n], 0, 0, 0); __builtin_amdgcn_s_setprio(0); } while (0)
; #define PG8_WAIT_V(n) asm volatile("s_waitcnt vmcnt(" #n ")" ::: "memory")
; #define PG8_WAIT_L(n) asm volatile("s_waitcnt lgkmcnt(" #n ")" ::: "memory")
; #define PG8_BAR __builtin_amdgcn_s_barrier()
; #define PG8_SCHED __builtin_amdgcn_sched_barrier(0)
; template <class Epi, bool ALIGN_EPI>
; __device__ __forceinline__ void gemm_phase(LAS unsigned char* lds, const Gemm g, const StaticOrder& S, const Epi& E, const int tid) {
;     ...
;             PG8_WAIT_V(8); PG8_WAIT_L(0); PG8_BAR; PG8_MMA(1, 0, At, B0); PG8_MMA(1, 1, At, B1); PG8_BAR; PG8_SCHED;
;             PG8_LDB(B0, 1, 0); PG8_LDB(B1, 1, 1); PG8_SCHED; PG8_LDA(At, 1, 0); PG8_STAGE(PG8_SA(0, 1), a2 + hstepA, voffA);
;             PG8_WAIT_V(8); PG8_WAIT_L(0); PG8_BAR; PG8_MMA(0, 0, At, B0); PG8_MMA(0, 1, At, B1); PG8_BAR; PG8_SCHED;
	s_barrier
	s_add_i32 s90, 0, 0x18000
	v_add_u32_e32 v0, s90, v160
	s_add_i32 s91, 0, 0x1c000
	ds_read_b128 v[132:135], v0
	ds_read_b128 v[136:139], v0 offset:1024
	ds_read_b128 v[152:155], v0 offset:2048
	ds_read_b128 v[156:159], v0 offset:3072
	v_add_u32_e32 v0, s91, v160
	ds_read_b128 v[162:165], v0
	ds_read_b128 v[166:169], v0 offset:1024
	ds_read_b128 v[170:173], v0 offset:2048
	ds_read_b128 v[174:177], v0 offset:3072
	s_add_u32 s54, s54, 0x4000
	s_addc_u32 s55, s55, 0
	s_mov_b32 m0, s74
	ds_read_b128 v[178:181], v161 offset:32768
	ds_read_b128 v[182:185], v161 offset:33792
	ds_read_b128 v[186:189], v161 offset:34816
	ds_read_b128 v[190:193], v161 offset:35840
	ds_read_b128 v[194:197], v161 offset:36864
	ds_read_b128 v[198:201], v161 offset:37888
	ds_read_b128 v[214:217], v161 offset:38912
	ds_read_b128 v[218:221], v161 offset:39936
	global_load_lds_dwordx4 v146, s[54:55]
	s_mov_b32 m0, s75
	s_nop 0
	global_load_lds_dwordx4 v142, s[54:55]
	s_waitcnt vmcnt(8) lgkmcnt(0)
	s_barrier


; #define PG8_MMA(ai, bj, At, Bt) do { __builtin_amdgcn_s_setprio(1); _Pragma("unroll") for (int m = 0; m < 4; ++m) _Pragma("unroll") for (int n = 0; n < 2; ++n) _Pragma("unroll") for (int k = 0; k < 2; ++k) \
;         acc[ai][bj][m][n] = __builtin_amdgcn_mfma_f32_16x16x32_bf16(Bt[n][k], At[m][k], acc[ai][bj][m][n], 0, 0, 0); __builtin_amdgcn_s_setprio(0); } while (0)
; #define PG8_WAIT_V(n) asm volatile("s_waitcnt vmcnt(" #n ")" ::: "memory")
; #define PG8_WAIT_L(n) asm volatile("s_waitcnt lgkmcnt(" #n ")" ::: "memory")
; #define PG8_BAR __builtin_amdgcn_s_barrier()
; #define PG8_SCHED __builtin_amdgcn_sched_barrier(0)
; template <class Epi, bool ALIGN_EPI>
; __device__ __forceinline__ void gemm_phase(LAS unsigned char* lds, const Gemm g, const StaticOrder& S, const Epi& E, const int tid) {
;     ...
;             PG8_WAIT_V(8); PG8_WAIT_L(0); PG8_BAR; PG8_MMA(0, 0, At, B0); PG8_MMA(0, 1, At, B1); PG8_BAR; PG8_SCHED;
	v_mfma_f32_16x16x32_bf16 v[88:91], v[132:135], v[178:181], v[88:91]
	v_mfma_f32_16x16x32_bf16 v[124:127], v[152:155], v[178:181], v[124:127]
	v_mfma_f32_16x16x32_bf16 v[52:55], v[132:135], v[186:189], v[52:55]
	v_mfma_f32_16x16x32_bf16 v[120:123], v[152:155], v[186:189], v[120:123]
	v_mfma_f32_16x16x32_bf16 v[40:43], v[132:135], v[194:197], v[40:43]
	v_mfma_f32_16x16x32_bf16 v[116:119], v[152:155], v[194:197], v[116:119]
	v_mfma_f32_16x16x32_bf16 v[36:39], v[132:135], v[214:217], v[36:39]
	v_mfma_f32_16x16x32_bf16 v[112:115], v[152:155], v[214:217], v[112:115]
	v_mfma_f32_16x16x32_bf16 v[88:91], v[136:139], v[182:185], v[88:91]
	v_mfma_f32_16x16x32_bf16 v[124:127], v[156:159], v[182:185], v[124:127]
	v_mfma_f32_16x16x32_bf16 v[52:55], v[136:139], v[190:193], v[52:55]
	v_mfma_f32_16x16x32_bf16 v[120:123], v[156:159], v[190:193], v[120:123]
	v_mfma_f32_16x16x32_bf16 v[40:43], v[136:139], v[198:201], v[40:43]
	v_mfma_f32_16x16x32_bf16 v[116:119], v[156:159], v[198:201], v[116:119]
	v_mfma_f32_16x16x32_bf16 v[36:39], v[136:139], v[218:221], v[36:39]
	v_mfma_f32_16x16x32_bf16 v[112:115], v[156:159], v[218:221], v[112:115]


; #define PG8_MMA(ai, bj, At, Bt) do { __builtin_amdgcn_s_setprio(1); _Pragma("unroll") for (int m = 0; m < 4; ++m) _Pragma("unroll") for (int n = 0; n < 2; ++n) _Pragma("unroll") for (int k = 0; k < 2; ++k) \
;         acc[ai][bj][m][n] = __builtin_amdgcn_mfma_f32_16x16x32_bf16(Bt[n][k], At[m][k], acc[ai][bj][m][n], 0, 0, 0); __builtin_amdgcn_s_setprio(0); } while (0)
; #define PG8_WAIT_V(n) asm volatile("s_waitcnt vmcnt(" #n ")" ::: "memory")
; #define PG8_WAIT_L(n) asm volatile("s_waitcnt lgkmcnt(" #n ")" ::: "memory")
; #define PG8_BAR __builtin_amdgcn_s_barrier()
; #define PG8_SCHED __builtin_amdgcn_sched_barrier(0)
; template <class Epi, bool ALIGN_EPI>
; __device__ __forceinline__ void gemm_phase(LAS unsigned char* lds, const Gemm g, const StaticOrder& S, const Epi& E, const int tid) {
;     ...
;             PG8_WAIT_V(8); PG8_WAIT_L(0); PG8_BAR; PG8_MMA(0, 0, At, B0); PG8_MMA(0, 1, At, B1); PG8_BAR; PG8_SCHED;
	v_mfma_f32_16x16x32_bf16 v[80:83], v[162:165], v[178:181], v[80:83]
	v_mfma_f32_16x16x32_bf16 v[128:131], v[170:173], v[178:181], v[128:131]
	v_mfma_f32_16x16x32_bf16 v[68:71], v[162:165], v[186:189], v[68:71]
	v_mfma_f32_16x16x32_bf16 v[108:111], v[170:173], v[186:189], v[108:111]
	v_mfma_f32_16x16x32_bf16 v[60:63], v[162:165], v[194:197], v[60:63]
	v_mfma_f32_16x16x32_bf16 v[104:107], v[170:173], v[194:197], v[104:107]
	v_mfma_f32_16x16x32_bf16 v[48:51], v[162:165], v[214:217], v[48:51]
	v_mfma_f32_16x16x32_bf16 v[100:103], v[170:173], v[214:217], v[100:103]
	v_mfma_f32_16x16x32_bf16 v[80:83], v[166:169], v[182:185], v[80:83]
	v_mfma_f32_16x16x32_bf16 v[128:131], v[174:177], v[182:185], v[128:131]
	v_mfma_f32_16x16x32_bf16 v[68:71], v[166:169], v[190:193], v[68:71]
	v_mfma_f32_16x16x32_bf16 v[108:111], v[174:177], v[190:193], v[108:111]
	v_mfma_f32_16x16x32_bf16 v[60:63], v[166:169], v[198:201], v[60:63]
	v_mfma_f32_16x16x32_bf16 v[104:107], v[174:177], v[198:201], v[104:107]
	v_mfma_f32_16x16x32_bf16 v[48:51], v[166:169], v[218:221], v[48:51]
	v_mfma_f32_16x16x32_bf16 v[100:103], v[174:177], v[218:221], v[100:103]

; #define PG8_STAGE(bufoff, gbase, voff) do { _Pragma("unroll") for (int _i = 0; _i < 2; ++_i) \
;         __builtin_amdgcn_global_load_lds((const unsigned*)((const char*)(gbase) + (voff)[_i]), (LAS unsigned*)(lds + (bufoff) + ldsw + _i * 8192), 16, 0, 0); } while (0)
; #define PG8_LDA(dst, b, h) do { _Pragma("unroll") for (int m = 0; m < 4; ++m) _Pragma("unroll") for (int k = 0; k < 2; ++k) dst[m][k] = *(const LAS bf16x8*)(lds + PG8_SA(b, h) + aoff + m * 2048 + k * 1024); } while (0)
; #define PG8_MMA(ai, bj, At, Bt) do { __builtin_amdgcn_s_setprio(1); _Pragma("unroll") for (int m = 0; m < 4; ++m) _Pragma("unroll") for (int n = 0; n < 2; ++n) _Pragma("unroll") for (int k = 0; k < 2; ++k) \
;         acc[ai][bj][m][n] = __builtin_amdgcn_mfma_f32_16x16x32_bf16(Bt[n][k], At[m][k], acc[ai][bj][m][n], 0, 0, 0); __builtin_amdgcn_s_setprio(0); } while (0)
; #define PG8_WAIT_V(n) asm volatile("s_waitcnt vmcnt(" #n ")" ::: "memory")
; #define PG8_WAIT_L(n) asm volatile("s_waitcnt lgkmcnt(" #n ")" ::: "memory")
; #define PG8_BAR __builtin_amdgcn_s_barrier()
; #define PG8_SCHED __builtin_amdgcn_sched_barrier(0)
; template <class Epi, bool ALIGN_EPI>
; __device__ __forceinline__ void gemm_phase(LAS unsigned char* lds, const Gemm g, const StaticOrder& S, const Epi& E, const int tid) {
;     ...
;             PG8_WAIT_V(8); PG8_WAIT_L(0); PG8_BAR; PG8_MMA(0, 0, At, B0); PG8_MMA(0, 1, At, B1); PG8_BAR; PG8_SCHED;
;             PG8_LDA(At, 1, 1); PG8_STAGE(PG8_SB(1, 0), b3, voffB); PG8_STAGE(PG8_SB(1, 1), b3 + hstepB, voffB); PG8_STAGE(PG8_SA(1, 0), a3, voffA);
;             PG8_WAIT_V(8); PG8_WAIT_L(0); PG8_BAR; PG8_MMA(1, 0, At, B0); PG8_MMA(1, 1, At, B1); PG8_BAR; PG8_SCHED;
	s_barrier
	s_add_u32 s54, s52, 0x8000
	s_addc_u32 s55, s53, 0
	s_add_i32 s90, s90, s71
	s_mov_b32 m0, s90
	ds_read_b128 v[178:181], v161 offset:49152
	ds_read_b128 v[182:185], v161 offset:50176
	ds_read_b128 v[186:189], v161 offset:51200
	ds_read_b128 v[190:193], v161 offset:52224
	ds_read_b128 v[194:197], v161 offset:53248
	ds_read_b128 v[198:201], v161 offset:54272
	ds_read_b128 v[214:217], v161 offset:55296
	ds_read_b128 v[218:221], v161 offset:56320
	global_load_lds_dwordx4 v144, s[54:55]
	s_add_i32 m0, s90, 0x2000
	s_add_u32 s52, s52, 0xc000
	s_addc_u32 s53, s53, 0
	global_load_lds_dwordx4 v140, s[54:55]
	s_add_i32 s54, s91, s71
	s_mov_b32 m0, s54
	s_nop 0
	global_load_lds_dwordx4 v144, s[52:53]
	s_add_i32 m0, s54, 0x2000
	s_nop 0
	global_load_lds_dwordx4 v140, s[52:53]
	s_mov_b32 m0, s79
	s_nop 0
	global_load_lds_dwordx4 v146, s[50:51]
	s_mov_b32 m0, s80
	s_nop 0
	global_load_lds_dwordx4 v142, s[50:51]
	s_waitcnt vmcnt(8) lgkmcnt(0)
	s_barrier


; #define PG8_MMA(ai, bj, At, Bt) do { __builtin_amdgcn_s_setprio(1); _Pragma("unroll") for (int m = 0; m < 4; ++m) _Pragma("unroll") for (int n = 0; n < 2; ++n) _Pragma("unroll") for (int k = 0; k < 2; ++k) \
;         acc[ai][bj][m][n] = __builtin_amdgcn_mfma_f32_16x16x32_bf16(Bt[n][k], At[m][k], acc[ai][bj][m][n], 0, 0, 0); __builtin_amdgcn_s_setprio(0); } while (0)
; #define PG8_WAIT_V(n) asm volatile("s_waitcnt vmcnt(" #n ")" ::: "memory")
; #define PG8_WAIT_L(n) asm volatile("s_waitcnt lgkmcnt(" #n ")" ::: "memory")
; #define PG8_BAR __builtin_amdgcn_s_barrier()
; #define PG8_SCHED __builtin_amdgcn_sched_barrier(0)
; template <class Epi, bool ALIGN_EPI>
; __device__ __forceinline__ void gemm_phase(LAS unsigned char* lds, const Gemm g, const StaticOrder& S, const Epi& E, const int tid) {
;     ...
;             PG8_WAIT_V(8); PG8_WAIT_L(0); PG8_BAR; PG8_MMA(1, 0, At, B0); PG8_MMA(1, 1, At, B1); PG8_BAR; PG8_SCHED;
	v_mfma_f32_16x16x32_bf16 v[24:27], v[132:135], v[178:181], v[24:27]
	v_mfma_f32_16x16x32_bf16 v[92:95], v[152:155], v[178:181], v[92:95]
	v_mfma_f32_16x16x32_bf16 v[16:19], v[132:135], v[186:189], v[16:19]
	v_mfma_f32_16x16x32_bf16 v[84:87], v[152:155], v[186:189], v[84:87]
	v_mfma_f32_16x16x32_bf16 v[6:9], v[132:135], v[194:197], v[8:11]
	v_mfma_f32_16x16x32_bf16 v[76:79], v[152:155], v[194:197], v[76:79]
	v_mfma_f32_16x16x32_bf16 v[2:5], v[132:135], v[214:217], v[2:5]
	v_mfma_f32_16x16x32_bf16 v[64:67], v[152:155], v[214:217], v[64:67]
	v_mfma_f32_16x16x32_bf16 v[24:27], v[136:139], v[182:185], v[24:27]
	v_mfma_f32_16x16x32_bf16 v[92:95], v[156:159], v[182:185], v[92:95]
	v_mfma_f32_16x16x32_bf16 v[16:19], v[136:139], v[190:193], v[16:19]
	v_mfma_f32_16x16x32_bf16 v[84:87], v[156:159], v[190:193], v[84:87]
	v_mfma_f32_16x16x32_bf16 v[8:11], v[136:139], v[198:201], v[6:9]
	v_mfma_f32_16x16x32_bf16 v[76:79], v[156:159], v[198:201], v[76:79]
	v_mfma_f32_16x16x32_bf16 v[4:7], v[136:139], v[218:221], v[2:5]
	v_mfma_f32_16x16x32_bf16 v[64:67], v[156:159], v[218:221], v[64:67]


; #define PG8_MMA(ai, bj, At, Bt) do { __builtin_amdgcn_s_setprio(1); _Pragma("unroll") for (int m = 0; m < 4; ++m) _Pragma("unroll") for (int n = 0; n < 2; ++n) _Pragma("unroll") for (int k = 0; k < 2; ++k) \
;         acc[ai][bj][m][n] = __builtin_amdgcn_mfma_f32_16x16x32_bf16(Bt[n][k], At[m][k], acc[ai][bj][m][n], 0, 0, 0); __builtin_amdgcn_s_setprio(0); } while (0)
; #define PG8_WAIT_V(n) asm volatile("s_waitcnt vmcnt(" #n ")" ::: "memory")
; #define PG8_WAIT_L(n) asm volatile("s_waitcnt lgkmcnt(" #n ")" ::: "memory")
; #define PG8_BAR __builtin_amdgcn_s_barrier()
; #define PG8_SCHED __builtin_amdgcn_sched_barrier(0)
; template <class Epi, bool ALIGN_EPI>
; __device__ __forceinline__ void gemm_phase(LAS unsigned char* lds, const Gemm g, const StaticOrder& S, const Epi& E, const int tid) {
;     ...
;             PG8_WAIT_V(8); PG8_WAIT_L(0); PG8_BAR; PG8_MMA(1, 0, At, B0); PG8_MMA(1, 1, At, B1); PG8_BAR; PG8_SCHED;
	v_mfma_f32_16x16x32_bf16 v[32:35], v[162:165], v[178:181], v[32:35]
	v_mfma_f32_16x16x32_bf16 v[72:75], v[170:173], v[178:181], v[72:75]
	v_mfma_f32_16x16x32_bf16 v[28:31], v[162:165], v[186:189], v[28:31]
	v_mfma_f32_16x16x32_bf16 v[96:99], v[170:173], v[186:189], v[96:99]
	v_mfma_f32_16x16x32_bf16 v[20:23], v[162:165], v[194:197], v[20:23]
	v_mfma_f32_16x16x32_bf16 v[56:59], v[170:173], v[194:197], v[56:59]
	v_mfma_f32_16x16x32_bf16 v[12:15], v[162:165], v[214:217], v[12:15]
	v_mfma_f32_16x16x32_bf16 v[44:47], v[170:173], v[214:217], v[44:47]
	v_mfma_f32_16x16x32_bf16 v[32:35], v[166:169], v[182:185], v[32:35]
	v_mfma_f32_16x16x32_bf16 v[72:75], v[174:177], v[182:185], v[72:75]
	v_mfma_f32_16x16x32_bf16 v[28:31], v[166:169], v[190:193], v[28:31]
	v_mfma_f32_16x16x32_bf16 v[96:99], v[174:177], v[190:193], v[96:99]
	v_mfma_f32_16x16x32_bf16 v[20:23], v[166:169], v[198:201], v[20:23]
	v_mfma_f32_16x16x32_bf16 v[56:59], v[174:177], v[198:201], v[56:59]
	v_mfma_f32_16x16x32_bf16 v[12:15], v[166:169], v[218:221], v[12:15]
	v_mfma_f32_16x16x32_bf16 v[44:47], v[174:177], v[218:221], v[44:47]

; #define PG8_MMA(ai, bj, At, Bt) do { __builtin_amdgcn_s_setprio(1); _Pragma("unroll") for (int m = 0; m < 4; ++m) _Pragma("unroll") for (int n = 0; n < 2; ++n) _Pragma("unroll") for (int k = 0; k < 2; ++k) \
;         acc[ai][bj][m][n] = __builtin_amdgcn_mfma_f32_16x16x32_bf16(Bt[n][k], At[m][k], acc[ai][bj][m][n], 0, 0, 0); __builtin_amdgcn_s_setprio(0); } while (0)
; #define PG8_WAIT_V(n) asm volatile("s_waitcnt vmcnt(" #n ")" ::: "memory")
; #define PG8_WAIT_L(n) asm volatile("s_waitcnt lgkmcnt(" #n ")" ::: "memory")
; #define PG8_BAR __builtin_amdgcn_s_barrier()
; #define PG8_SCHED __builtin_amdgcn_sched_barrier(0)
; template <class Epi, bool ALIGN_EPI>
; __device__ __forceinline__ void gemm_phase(LAS unsigned char* lds, const Gemm g, const StaticOrder& S, const Epi& E, const int tid) {
;     ...
;             PG8_WAIT_V(8); PG8_WAIT_L(0); PG8_BAR; PG8_MMA(1, 0, At, B0); PG8_MMA(1, 1, At, B1); PG8_BAR; PG8_SCHED;
;         }
;         if constexpr (ALIGN_EPI) { if (wr == 0) PG8_BAR; }
	s_barrier
	s_add_i32 s89, s89, 2
	s_add_u32 s48, s48, 0x10000
	s_addc_u32 s49, s49, 0
	s_add_u32 vcc_hi, vcc_hi, 0x10000
	s_addc_u32 s88, s88, 0
	s_cmp_gt_u32 s89, 29
	s_cbranch_scc0 .LBB0_211
	s_and_b64 vcc, exec, s[22:23]
	s_cbranch_vccz .LBB0_214
	s_barrier

; #define PG8_STAGE(bufoff, gbase, voff) do { _Pragma("unroll") for (int _i = 0; _i < 2; ++_i) \
;         __builtin_amdgcn_global_load_lds((const unsigned*)((const char*)(gbase) + (voff)[_i]), (LAS unsigned*)(lds + (bufoff) + ldsw + _i * 8192), 16, 0, 0); } while (0)
; #define PG8_LDA(dst, b, h) do { _Pragma("unroll") for (int m = 0; m < 4; ++m) _Pragma("unroll") for (int k = 0; k < 2; ++k) dst[m][k] = *(const LAS bf16x8*)(lds + PG8_SA(b, h) + aoff + m * 2048 + k * 1024); } while (0)
; #define PG8_LDB(dst, b, h) do { _Pragma("unroll") for (int n = 0; n < 2; ++n) _Pragma("unroll") for (int k = 0; k < 2; ++k) dst[n][k] = *(const LAS bf16x8*)(lds + PG8_SB(b, h) + boff + n * 2048 + k * 1024); } while (0)
; #define PG8_MMA(ai, bj, At, Bt) do { __builtin_amdgcn_s_setprio(1); _Pragma("unroll") for (int m = 0; m < 4; ++m) _Pragma("unroll") for (int n = 0; n < 2; ++n) _Pragma("unroll") for (int k = 0; k < 2; ++k) \
;         acc[ai][bj][m][n] = __builtin_amdgcn_mfma_f32_16x16x32_bf16(Bt[n][k], At[m][k], acc[ai][bj][m][n], 0, 0, 0); __builtin_amdgcn_s_setprio(0); } while (0)
; #define PG8_WAIT_V(n) asm volatile("s_waitcnt vmcnt(" #n ")" ::: "memory")
; #define PG8_WAIT_L(n) asm volatile("s_waitcnt lgkmcnt(" #n ")" ::: "memory")
; #define PG8_BAR __builtin_amdgcn_s_barrier()
; #define PG8_SCHED __builtin_amdgcn_sched_barrier(0)
; template <class Epi, bool ALIGN_EPI>
; __device__ __forceinline__ void gemm_phase(LAS unsigned char* lds, const Gemm g, const StaticOrder& S, const Epi& E, const int tid) {
;     ...
;         for (int t = 0; t < nt; t += 2) {
;             const bool last = (t == nt - 2);
;             const char* a1 = cA + (size_t)(t + 1) * kstepA;
;             const char* a2 = last ? nA : cA + (size_t)(t + 2) * kstepA; const char* b2 = last ? nB : cB + (size_t)(t + 2) * kstepB;
;             const char* a3 = a2 + kstepA; const char* b3 = b2 + kstepB;
;             PG8_LDB(B0, 0, 0); PG8_LDB(B1, 0, 1); PG8_SCHED; PG8_LDA(At, 0, 0); PG8_STAGE(PG8_SA(1, 1), a1 + hstepA, voffA);
;             PG8_WAIT_V(8); PG8_WAIT_L(0); PG8_BAR; PG8_MMA(0, 0, At, B0); PG8_MMA(0, 1, At, B1); PG8_BAR; PG8_SCHED;
.LBB0_294:
	s_add_u32 s22, s10, 0x4000
	s_addc_u32 s23, s11, 0
	s_cmpk_eq_i32 s86, 0x54
	s_cselect_b32 s42, s48, s22
	s_cselect_b32 s43, s49, s23
	s_cselect_b32 s34, s50, s84
	s_cselect_b32 s35, s51, s85
	s_add_u32 s22, s42, 0x8000
	s_addc_u32 s23, s43, 0
	s_add_i32 s87, 0, 0x10000
	v_add_u32_e32 v0, s87, v154
	s_add_i32 s90, 0, 0x14000
	s_waitcnt lgkmcnt(0)
	ds_read_b128 v[132:135], v0
	ds_read_b128 v[148:151], v0 offset:1024
	ds_read_b128 v[156:159], v0 offset:2048
	ds_read_b128 v[160:163], v0 offset:3072
	v_add_u32_e32 v0, s90, v154
	ds_read_b128 v[164:167], v0
	ds_read_b128 v[168:171], v0 offset:1024
	ds_read_b128 v[172:175], v0 offset:2048
	ds_read_b128 v[176:179], v0 offset:3072
	s_add_i32 m0, s57, 0xc000
	ds_read_b128 v[180:183], v155
	ds_read_b128 v[184:187], v155 offset:1024
	ds_read_b128 v[188:191], v155 offset:2048
	ds_read_b128 v[192:195], v155 offset:3072
	ds_read_b128 v[196:199], v155 offset:4096
	ds_read_b128 v[214:217], v155 offset:5120
	ds_read_b128 v[218:221], v155 offset:6144
	ds_read_b128 v[222:225], v155 offset:7168
	global_load_lds_dwordx4 v144, s[10:11]
	s_add_i32 m0, s57, 0xe000
	s_nop 0
	global_load_lds_dwordx4 v146, s[10:11]
	s_waitcnt vmcnt(8) lgkmcnt(0)
	s_barrier


; #define PG8_MMA(ai, bj, At, Bt) do { __builtin_amdgcn_s_setprio(1); _Pragma("unroll") for (int m = 0; m < 4; ++m) _Pragma("unroll") for (int n = 0; n < 2; ++n) _Pragma("unroll") for (int k = 0; k < 2; ++k) \
;         acc[ai][bj][m][n] = __builtin_amdgcn_mfma_f32_16x16x32_bf16(Bt[n][k], At[m][k], acc[ai][bj][m][n], 0, 0, 0); __builtin_amdgcn_s_setprio(0); } while (0)
; #define PG8_WAIT_V(n) asm volatile("s_waitcnt vmcnt(" #n ")" ::: "memory")
; #define PG8_WAIT_L(n) asm volatile("s_waitcnt lgkmcnt(" #n ")" ::: "memory")
; #define PG8_BAR __builtin_amdgcn_s_barrier()
; #define PG8_SCHED __builtin_amdgcn_sched_barrier(0)
; template <class Epi, bool ALIGN_EPI>
; __device__ __forceinline__ void gemm_phase(LAS unsigned char* lds, const Gemm g, const StaticOrder& S, const Epi& E, const int tid) {
;     ...
;             PG8_WAIT_V(8); PG8_WAIT_L(0); PG8_BAR; PG8_MMA(0, 0, At, B0); PG8_MMA(0, 1, At, B1); PG8_BAR; PG8_SCHED;
	v_mfma_f32_16x16x32_bf16 v[8:11], v[132:135], v[180:183], v[8:11]
	v_mfma_f32_16x16x32_bf16 v[56:59], v[156:159], v[180:183], v[56:59]
	v_mfma_f32_16x16x32_bf16 v[52:55], v[132:135], v[188:191], v[52:55]
	v_mfma_f32_16x16x32_bf16 v[48:51], v[156:159], v[188:191], v[48:51]
	v_mfma_f32_16x16x32_bf16 v[44:47], v[132:135], v[196:199], v[44:47]
	v_mfma_f32_16x16x32_bf16 v[40:43], v[156:159], v[196:199], v[40:43]
	v_mfma_f32_16x16x32_bf16 v[36:39], v[132:135], v[218:221], v[36:39]
	v_mfma_f32_16x16x32_bf16 v[32:35], v[156:159], v[218:221], v[32:35]
	v_mfma_f32_16x16x32_bf16 v[8:11], v[148:151], v[184:187], v[8:11]
	v_mfma_f32_16x16x32_bf16 v[56:59], v[160:163], v[184:187], v[56:59]
	v_mfma_f32_16x16x32_bf16 v[52:55], v[148:151], v[192:195], v[52:55]
	v_mfma_f32_16x16x32_bf16 v[48:51], v[160:163], v[192:195], v[48:51]
	v_mfma_f32_16x16x32_bf16 v[44:47], v[148:151], v[214:217], v[44:47]
	v_mfma_f32_16x16x32_bf16 v[40:43], v[160:163], v[214:217], v[40:43]
	v_mfma_f32_16x16x32_bf16 v[36:39], v[148:151], v[222:225], v[36:39]
	v_mfma_f32_16x16x32_bf16 v[32:35], v[160:163], v[222:225], v[32:35]


; #define PG8_MMA(ai, bj, At, Bt) do { __builtin_amdgcn_s_setprio(1); _Pragma("unroll") for (int m = 0; m < 4; ++m) _Pragma("unroll") for (int n = 0; n < 2; ++n) _Pragma("unroll") for (int k = 0; k < 2; ++k) \
;         acc[ai][bj][m][n] = __builtin_amdgcn_mfma_f32_16x16x32_bf16(Bt[n][k], At[m][k], acc[ai][bj][m][n], 0, 0, 0); __builtin_amdgcn_s_setprio(0); } while (0)
; #define PG8_WAIT_V(n) asm volatile("s_waitcnt vmcnt(" #n ")" ::: "memory")
; #define PG8_WAIT_L(n) asm volatile("s_waitcnt lgkmcnt(" #n ")" ::: "memory")
; #define PG8_BAR __builtin_amdgcn_s_barrier()
; #define PG8_SCHED __builtin_amdgcn_sched_barrier(0)
; template <class Epi, bool ALIGN_EPI>
; __device__ __forceinline__ void gemm_phase(LAS unsigned char* lds, const Gemm g, const StaticOrder& S, const Epi& E, const int tid) {
;     ...
;             PG8_WAIT_V(8); PG8_WAIT_L(0); PG8_BAR; PG8_MMA(0, 0, At, B0); PG8_MMA(0, 1, At, B1); PG8_BAR; PG8_SCHED;
	v_mfma_f32_16x16x32_bf16 v[2:5], v[164:167], v[180:183], v[4:7]
	v_mfma_f32_16x16x32_bf16 v[28:31], v[172:175], v[180:183], v[28:31]
	v_mfma_f32_16x16x32_bf16 v[96:99], v[164:167], v[188:191], v[96:99]
	v_mfma_f32_16x16x32_bf16 v[92:95], v[172:175], v[188:191], v[92:95]
	v_mfma_f32_16x16x32_bf16 v[88:91], v[164:167], v[196:199], v[88:91]
	v_mfma_f32_16x16x32_bf16 v[84:87], v[172:175], v[196:199], v[84:87]
	v_mfma_f32_16x16x32_bf16 v[80:83], v[164:167], v[218:221], v[80:83]
	v_mfma_f32_16x16x32_bf16 v[76:79], v[172:175], v[218:221], v[76:79]
	v_mfma_f32_16x16x32_bf16 v[2:5], v[168:171], v[184:187], v[2:5]
	v_mfma_f32_16x16x32_bf16 v[28:31], v[176:179], v[184:187], v[28:31]
	v_mfma_f32_16x16x32_bf16 v[96:99], v[168:171], v[192:195], v[96:99]
	v_mfma_f32_16x16x32_bf16 v[92:95], v[176:179], v[192:195], v[92:95]
	v_mfma_f32_16x16x32_bf16 v[88:91], v[168:171], v[214:217], v[88:91]
	v_mfma_f32_16x16x32_bf16 v[84:87], v[176:179], v[214:217], v[84:87]
	v_mfma_f32_16x16x32_bf16 v[80:83], v[168:171], v[222:225], v[80:83]
	v_mfma_f32_16x16x32_bf16 v[76:79], v[176:179], v[222:225], v[76:79]

; #define PG8_STAGE(bufoff, gbase, voff) do { _Pragma("unroll") for (int _i = 0; _i < 2; ++_i) \
;         __builtin_amdgcn_global_load_lds((const unsigned*)((const char*)(gbase) + (voff)[_i]), (LAS unsigned*)(lds + (bufoff) + ldsw + _i * 8192), 16, 0, 0); } while (0)
; #define PG8_LDA(dst, b, h) do { _Pragma("unroll") for (int m = 0; m < 4; ++m) _Pragma("unroll") for (int k = 0; k < 2; ++k) dst[m][k] = *(const LAS bf16x8*)(lds + PG8_SA(b, h) + aoff + m * 2048 + k * 1024); } while (0)
; #define PG8_MMA(ai, bj, At, Bt) do { __builtin_amdgcn_s_setprio(1); _Pragma("unroll") for (int m = 0; m < 4; ++m) _Pragma("unroll") for (int n = 0; n < 2; ++n) _Pragma("unroll") for (int k = 0; k < 2; ++k) \
;         acc[ai][bj][m][n] = __builtin_amdgcn_mfma_f32_16x16x32_bf16(Bt[n][k], At[m][k], acc[ai][bj][m][n], 0, 0, 0); __builtin_amdgcn_s_setprio(0); } while (0)
; #define PG8_WAIT_V(n) asm volatile("s_waitcnt vmcnt(" #n ")" ::: "memory")
; #define PG8_WAIT_L(n) asm volatile("s_waitcnt lgkmcnt(" #n ")" ::: "memory")
; #define PG8_BAR __builtin_amdgcn_s_barrier()
; #define PG8_SCHED __builtin_amdgcn_sched_barrier(0)
; template <class Epi, bool ALIGN_EPI>
; __device__ __forceinline__ void gemm_phase(LAS unsigned char* lds, const Gemm g, const StaticOrder& S, const Epi& E, const int tid) {
;     ...
;             PG8_WAIT_V(8); PG8_WAIT_L(0); PG8_BAR; PG8_MMA(0, 0, At, B0); PG8_MMA(0, 1, At, B1); PG8_BAR; PG8_SCHED;
;             PG8_LDA(At, 0, 1); PG8_STAGE(PG8_SB(0, 0), b2, voffB); PG8_STAGE(PG8_SB(0, 1), b2 + hstepB, voffB); PG8_STAGE(PG8_SA(0, 0), a2, voffA);
;             PG8_WAIT_V(8); PG8_WAIT_L(0); PG8_BAR; PG8_MMA(1, 0, At, B0); PG8_MMA(1, 1, At, B1); PG8_BAR; PG8_SCHED;
	s_barrier
	s_add_i32 s87, s87, s56
	s_mov_b32 m0, s87
	ds_read_b128 v[180:183], v155 offset:16384
	ds_read_b128 v[184:187], v155 offset:17408
	ds_read_b128 v[188:191], v155 offset:18432
	ds_read_b128 v[192:195], v155 offset:19456
	ds_read_b128 v[196:199], v155 offset:20480
	ds_read_b128 v[214:217], v155 offset:21504
	ds_read_b128 v[218:221], v155 offset:22528
	ds_read_b128 v[222:225], v155 offset:23552
	global_load_lds_dwordx4 v140, s[34:35]
	s_add_i32 m0, s87, 0x2000
	s_add_u32 s88, s34, 0x4000
	s_addc_u32 s89, s35, 0
	s_add_i32 s87, s90, s56
	global_load_lds_dwordx4 v136, s[34:35]
	s_mov_b32 m0, s87
	s_nop 0
	global_load_lds_dwordx4 v140, s[88:89]
	s_add_i32 m0, s87, 0x2000
	s_nop 0
	global_load_lds_dwordx4 v136, s[88:89]
	s_mov_b32 m0, s57
	s_nop 0
	global_load_lds_dwordx4 v142, s[42:43]
	s_mov_b32 m0, s60
	s_nop 0
	global_load_lds_dwordx4 v138, s[42:43]
	s_waitcnt vmcnt(8) lgkmcnt(0)
	s_barrier


; #define PG8_MMA(ai, bj, At, Bt) do { __builtin_amdgcn_s_setprio(1); _Pragma("unroll") for (int m = 0; m < 4; ++m) _Pragma("unroll") for (int n = 0; n < 2; ++n) _Pragma("unroll") for (int k = 0; k < 2; ++k) \
;         acc[ai][bj][m][n] = __builtin_amdgcn_mfma_f32_16x16x32_bf16(Bt[n][k], At[m][k], acc[ai][bj][m][n], 0, 0, 0); __builtin_amdgcn_s_setprio(0); } while (0)
; #define PG8_WAIT_V(n) asm volatile("s_waitcnt vmcnt(" #n ")" ::: "memory")
; #define PG8_WAIT_L(n) asm volatile("s_waitcnt lgkmcnt(" #n ")" ::: "memory")
; #define PG8_BAR __builtin_amdgcn_s_barrier()
; #define PG8_SCHED __builtin_amdgcn_sched_barrier(0)
; template <class Epi, bool ALIGN_EPI>
; __device__ __forceinline__ void gemm_phase(LAS unsigned char* lds, const Gemm g, const StaticOrder& S, const Epi& E, const int tid) {
;     ...
;             PG8_WAIT_V(8); PG8_WAIT_L(0); PG8_BAR; PG8_MMA(1, 0, At, B0); PG8_MMA(1, 1, At, B1); PG8_BAR; PG8_SCHED;
	v_mfma_f32_16x16x32_bf16 v[24:27], v[132:135], v[180:183], v[24:27]
	v_mfma_f32_16x16x32_bf16 v[20:23], v[156:159], v[180:183], v[20:23]
	v_mfma_f32_16x16x32_bf16 v[64:67], v[132:135], v[188:191], v[64:67]
	v_mfma_f32_16x16x32_bf16 v[72:75], v[156:159], v[188:191], v[72:75]
	v_mfma_f32_16x16x32_bf16 v[16:19], v[132:135], v[196:199], v[16:19]
	v_mfma_f32_16x16x32_bf16 v[12:15], v[156:159], v[196:199], v[12:15]
	v_mfma_f32_16x16x32_bf16 v[60:63], v[132:135], v[218:221], v[60:63]
	v_mfma_f32_16x16x32_bf16 v[68:71], v[156:159], v[218:221], v[68:71]
	v_mfma_f32_16x16x32_bf16 v[24:27], v[148:151], v[184:187], v[24:27]
	v_mfma_f32_16x16x32_bf16 v[20:23], v[160:163], v[184:187], v[20:23]
	v_mfma_f32_16x16x32_bf16 v[64:67], v[148:151], v[192:195], v[64:67]
	v_mfma_f32_16x16x32_bf16 v[72:75], v[160:163], v[192:195], v[72:75]
	v_mfma_f32_16x16x32_bf16 v[16:19], v[148:151], v[214:217], v[16:19]
	v_mfma_f32_16x16x32_bf16 v[12:15], v[160:163], v[214:217], v[12:15]
	v_mfma_f32_16x16x32_bf16 v[60:63], v[148:151], v[222:225], v[60:63]
	v_mfma_f32_16x16x32_bf16 v[68:71], v[160:163], v[222:225], v[68:71]


; #define PG8_MMA(ai, bj, At, Bt) do { __builtin_amdgcn_s_setprio(1); _Pragma("unroll") for (int m = 0; m < 4; ++m) _Pragma("unroll") for (int n = 0; n < 2; ++n) _Pragma("unroll") for (int k = 0; k < 2; ++k) \
;         acc[ai][bj][m][n] = __builtin_amdgcn_mfma_f32_16x16x32_bf16(Bt[n][k], At[m][k], acc[ai][bj][m][n], 0, 0, 0); __builtin_amdgcn_s_setprio(0); } while (0)
; #define PG8_WAIT_V(n) asm volatile("s_waitcnt vmcnt(" #n ")" ::: "memory")
; #define PG8_WAIT_L(n) asm volatile("s_waitcnt lgkmcnt(" #n ")" ::: "memory")
; #define PG8_BAR __builtin_amdgcn_s_barrier()
; #define PG8_SCHED __builtin_amdgcn_sched_barrier(0)
; template <class Epi, bool ALIGN_EPI>
; __device__ __forceinline__ void gemm_phase(LAS unsigned char* lds, const Gemm g, const StaticOrder& S, const Epi& E, const int tid) {
;     ...
;             PG8_WAIT_V(8); PG8_WAIT_L(0); PG8_BAR; PG8_MMA(1, 0, At, B0); PG8_MMA(1, 1, At, B1); PG8_BAR; PG8_SCHED;
	v_mfma_f32_16x16x32_bf16 v[128:131], v[164:167], v[180:183], v[128:131]
	v_mfma_f32_16x16x32_bf16 v[124:127], v[172:175], v[180:183], v[124:127]
	v_mfma_f32_16x16x32_bf16 v[120:123], v[164:167], v[188:191], v[120:123]
	v_mfma_f32_16x16x32_bf16 v[116:119], v[172:175], v[188:191], v[116:119]
	v_mfma_f32_16x16x32_bf16 v[112:115], v[164:167], v[196:199], v[112:115]
	v_mfma_f32_16x16x32_bf16 v[108:111], v[172:175], v[196:199], v[108:111]
	v_mfma_f32_16x16x32_bf16 v[104:107], v[164:167], v[218:221], v[104:107]
	v_mfma_f32_16x16x32_bf16 v[100:103], v[172:175], v[218:221], v[100:103]
	v_mfma_f32_16x16x32_bf16 v[128:131], v[168:171], v[184:187], v[128:131]
	v_mfma_f32_16x16x32_bf16 v[124:127], v[176:179], v[184:187], v[124:127]
	v_mfma_f32_16x16x32_bf16 v[120:123], v[168:171], v[192:195], v[120:123]
	v_mfma_f32_16x16x32_bf16 v[116:119], v[176:179], v[192:195], v[116:119]
	v_mfma_f32_16x16x32_bf16 v[112:115], v[168:171], v[214:217], v[112:115]
	v_mfma_f32_16x16x32_bf16 v[108:111], v[176:179], v[214:217], v[108:111]
	v_mfma_f32_16x16x32_bf16 v[104:107], v[168:171], v[222:225], v[104:107]
	v_mfma_f32_16x16x32_bf16 v[100:103], v[176:179], v[222:225], v[100:103]

; #define PG8_STAGE(bufoff, gbase, voff) do { _Pragma("unroll") for (int _i = 0; _i < 2; ++_i) \
;         __builtin_amdgcn_global_load_lds((const unsigned*)((const char*)(gbase) + (voff)[_i]), (LAS unsigned*)(lds + (bufoff) + ldsw + _i * 8192), 16, 0, 0); } while (0)
; #define PG8_LDA(dst, b, h) do { _Pragma("unroll") for (int m = 0; m < 4; ++m) _Pragma("unroll") for (int k = 0; k < 2; ++k) dst[m][k] = *(const LAS bf16x8*)(lds + PG8_SA(b, h) + aoff + m * 2048 + k * 1024); } while (0)
; #define PG8_LDB(dst, b, h) do { _Pragma("unroll") for (int n = 0; n < 2; ++n) _Pragma("unroll") for (int k = 0; k < 2; ++k) dst[n][k] = *(const LAS bf16x8*)(lds + PG8_SB(b, h) + boff + n * 2048 + k * 1024); } while (0)
; #define PG8_MMA(ai, bj, At, Bt) do { __builtin_amdgcn_s_setprio(1); _Pragma("unroll") for (int m = 0; m < 4; ++m) _Pragma("unroll") for (int n = 0; n < 2; ++n) _Pragma("unroll") for (int k = 0; k < 2; ++k) \
;         acc[ai][bj][m][n] = __builtin_amdgcn_mfma_f32_16x16x32_bf16(Bt[n][k], At[m][k], acc[ai][bj][m][n], 0, 0, 0); __builtin_amdgcn_s_setprio(0); } while (0)
; #define PG8_WAIT_V(n) asm volatile("s_waitcnt vmcnt(" #n ")" ::: "memory")
; #define PG8_WAIT_L(n) asm volatile("s_waitcnt lgkmcnt(" #n ")" ::: "memory")
; #define PG8_BAR __builtin_amdgcn_s_barrier()
; #define PG8_SCHED __builtin_amdgcn_sched_barrier(0)
; template <class Epi, bool ALIGN_EPI>
; __device__ __forceinline__ void gemm_phase(LAS unsigned char* lds, const Gemm g, const StaticOrder& S, const Epi& E, const int tid) {
;     ...
;             PG8_WAIT_V(8); PG8_WAIT_L(0); PG8_BAR; PG8_MMA(1, 0, At, B0); PG8_MMA(1, 1, At, B1); PG8_BAR; PG8_SCHED;
;             PG8_LDB(B0, 1, 0); PG8_LDB(B1, 1, 1); PG8_SCHED; PG8_LDA(At, 1, 0); PG8_STAGE(PG8_SA(0, 1), a2 + hstepA, voffA);
;             PG8_WAIT_V(8); PG8_WAIT_L(0); PG8_BAR; PG8_MMA(0, 0, At, B0); PG8_MMA(0, 1, At, B1); PG8_BAR; PG8_SCHED;
	s_barrier
	s_add_i32 s87, 0, 0x18000
	v_add_u32_e32 v0, s87, v154
	s_add_i32 s88, 0, 0x1c000
	ds_read_b128 v[132:135], v0
	ds_read_b128 v[148:151], v0 offset:1024
	ds_read_b128 v[156:159], v0 offset:2048
	ds_read_b128 v[160:163], v0 offset:3072
	v_add_u32_e32 v0, s88, v154
	ds_read_b128 v[164:167], v0
	ds_read_b128 v[168:171], v0 offset:1024
	ds_read_b128 v[172:175], v0 offset:2048
	ds_read_b128 v[176:179], v0 offset:3072
	s_add_u32 s42, s42, 0x4000
	s_addc_u32 s43, s43, 0
	s_mov_b32 m0, s61
	ds_read_b128 v[180:183], v155 offset:32768
	ds_read_b128 v[184:187], v155 offset:33792
	ds_read_b128 v[188:191], v155 offset:34816
	ds_read_b128 v[192:195], v155 offset:35840
	ds_read_b128 v[196:199], v155 offset:36864
	ds_read_b128 v[214:217], v155 offset:37888
	ds_read_b128 v[218:221], v155 offset:38912
	ds_read_b128 v[222:225], v155 offset:39936
	global_load_lds_dwordx4 v142, s[42:43]
	s_mov_b32 m0, s71
	s_nop 0
	global_load_lds_dwordx4 v138, s[42:43]
	s_waitcnt vmcnt(8) lgkmcnt(0)
	s_barrier


; #define PG8_MMA(ai, bj, At, Bt) do { __builtin_amdgcn_s_setprio(1); _Pragma("unroll") for (int m = 0; m < 4; ++m) _Pragma("unroll") for (int n = 0; n < 2; ++n) _Pragma("unroll") for (int k = 0; k < 2; ++k) \
;         acc[ai][bj][m][n] = __builtin_amdgcn_mfma_f32_16x16x32_bf16(Bt[n][k], At[m][k], acc[ai][bj][m][n], 0, 0, 0); __builtin_amdgcn_s_setprio(0); } while (0)
; #define PG8_WAIT_V(n) asm volatile("s_waitcnt vmcnt(" #n ")" ::: "memory")
; #define PG8_WAIT_L(n) asm volatile("s_waitcnt lgkmcnt(" #n ")" ::: "memory")
; #define PG8_BAR __builtin_amdgcn_s_barrier()
; #define PG8_SCHED __builtin_amdgcn_sched_barrier(0)
; template <class Epi, bool ALIGN_EPI>
; __device__ __forceinline__ void gemm_phase(LAS unsigned char* lds, const Gemm g, const StaticOrder& S, const Epi& E, const int tid) {
;     ...
;             PG8_WAIT_V(8); PG8_WAIT_L(0); PG8_BAR; PG8_MMA(0, 0, At, B0); PG8_MMA(0, 1, At, B1); PG8_BAR; PG8_SCHED;
	v_mfma_f32_16x16x32_bf16 v[6:9], v[132:135], v[180:183], v[8:11]
	v_mfma_f32_16x16x32_bf16 v[56:59], v[156:159], v[180:183], v[56:59]
	v_mfma_f32_16x16x32_bf16 v[52:55], v[132:135], v[188:191], v[52:55]
	v_mfma_f32_16x16x32_bf16 v[48:51], v[156:159], v[188:191], v[48:51]
	v_mfma_f32_16x16x32_bf16 v[44:47], v[132:135], v[196:199], v[44:47]
	v_mfma_f32_16x16x32_bf16 v[40:43], v[156:159], v[196:199], v[40:43]
	v_mfma_f32_16x16x32_bf16 v[36:39], v[132:135], v[218:221], v[36:39]
	v_mfma_f32_16x16x32_bf16 v[32:35], v[156:159], v[218:221], v[32:35]
	v_mfma_f32_16x16x32_bf16 v[8:11], v[148:151], v[184:187], v[6:9]
	v_mfma_f32_16x16x32_bf16 v[56:59], v[160:163], v[184:187], v[56:59]
	v_mfma_f32_16x16x32_bf16 v[52:55], v[148:151], v[192:195], v[52:55]
	v_mfma_f32_16x16x32_bf16 v[48:51], v[160:163], v[192:195], v[48:51]
	v_mfma_f32_16x16x32_bf16 v[44:47], v[148:151], v[214:217], v[44:47]
	v_mfma_f32_16x16x32_bf16 v[40:43], v[160:163], v[214:217], v[40:43]
	v_mfma_f32_16x16x32_bf16 v[36:39], v[148:151], v[222:225], v[36:39]
	v_mfma_f32_16x16x32_bf16 v[32:35], v[160:163], v[222:225], v[32:35]


; #define PG8_MMA(ai, bj, At, Bt) do { __builtin_amdgcn_s_setprio(1); _Pragma("unroll") for (int m = 0; m < 4; ++m) _Pragma("unroll") for (int n = 0; n < 2; ++n) _Pragma("unroll") for (int k = 0; k < 2; ++k) \
;         acc[ai][bj][m][n] = __builtin_amdgcn_mfma_f32_16x16x32_bf16(Bt[n][k], At[m][k], acc[ai][bj][m][n], 0, 0, 0); __builtin_amdgcn_s_setprio(0); } while (0)
; #define PG8_WAIT_V(n) asm volatile("s_waitcnt vmcnt(" #n ")" ::: "memory")
; #define PG8_WAIT_L(n) asm volatile("s_waitcnt lgkmcnt(" #n ")" ::: "memory")
; #define PG8_BAR __builtin_amdgcn_s_barrier()
; #define PG8_SCHED __builtin_amdgcn_sched_barrier(0)
; template <class Epi, bool ALIGN_EPI>
; __device__ __forceinline__ void gemm_phase(LAS unsigned char* lds, const Gemm g, const StaticOrder& S, const Epi& E, const int tid) {
;     ...
;             PG8_WAIT_V(8); PG8_WAIT_L(0); PG8_BAR; PG8_MMA(0, 0, At, B0); PG8_MMA(0, 1, At, B1); PG8_BAR; PG8_SCHED;
	v_mfma_f32_16x16x32_bf16 v[2:5], v[164:167], v[180:183], v[2:5]
	v_mfma_f32_16x16x32_bf16 v[28:31], v[172:175], v[180:183], v[28:31]
	v_mfma_f32_16x16x32_bf16 v[96:99], v[164:167], v[188:191], v[96:99]
	v_mfma_f32_16x16x32_bf16 v[92:95], v[172:175], v[188:191], v[92:95]
	v_mfma_f32_16x16x32_bf16 v[88:91], v[164:167], v[196:199], v[88:91]
	v_mfma_f32_16x16x32_bf16 v[84:87], v[172:175], v[196:199], v[84:87]
	v_mfma_f32_16x16x32_bf16 v[80:83], v[164:167], v[218:221], v[80:83]
	v_mfma_f32_16x16x32_bf16 v[76:79], v[172:175], v[218:221], v[76:79]
	v_mfma_f32_16x16x32_bf16 v[4:7], v[168:171], v[184:187], v[2:5]
	v_mfma_f32_16x16x32_bf16 v[28:31], v[176:179], v[184:187], v[28:31]
	v_mfma_f32_16x16x32_bf16 v[96:99], v[168:171], v[192:195], v[96:99]
	v_mfma_f32_16x16x32_bf16 v[92:95], v[176:179], v[192:195], v[92:95]
	v_mfma_f32_16x16x32_bf16 v[88:91], v[168:171], v[214:217], v[88:91]
	v_mfma_f32_16x16x32_bf16 v[84:87], v[176:179], v[214:217], v[84:87]
	v_mfma_f32_16x16x32_bf16 v[80:83], v[168:171], v[222:225], v[80:83]
	v_mfma_f32_16x16x32_bf16 v[76:79], v[176:179], v[222:225], v[76:79]

; #define PG8_STAGE(bufoff, gbase, voff) do { _Pragma("unroll") for (int _i = 0; _i < 2; ++_i) \
;         __builtin_amdgcn_global_load_lds((const unsigned*)((const char*)(gbase) + (voff)[_i]), (LAS unsigned*)(lds + (bufoff) + ldsw + _i * 8192), 16, 0, 0); } while (0)
; #define PG8_LDA(dst, b, h) do { _Pragma("unroll") for (int m = 0; m < 4; ++m) _Pragma("unroll") for (int k = 0; k < 2; ++k) dst[m][k] = *(const LAS bf16x8*)(lds + PG8_SA(b, h) + aoff + m * 2048 + k * 1024); } while (0)
; #define PG8_MMA(ai, bj, At, Bt) do { __builtin_amdgcn_s_setprio(1); _Pragma("unroll") for (int m = 0; m < 4; ++m) _Pragma("unroll") for (int n = 0; n < 2; ++n) _Pragma("unroll") for (int k = 0; k < 2; ++k) \
;         acc[ai][bj][m][n] = __builtin_amdgcn_mfma_f32_16x16x32_bf16(Bt[n][k], At[m][k], acc[ai][bj][m][n], 0, 0, 0); __builtin_amdgcn_s_setprio(0); } while (0)
; #define PG8_WAIT_V(n) asm volatile("s_waitcnt vmcnt(" #n ")" ::: "memory")
; #define PG8_WAIT_L(n) asm volatile("s_waitcnt lgkmcnt(" #n ")" ::: "memory")
; #define PG8_BAR __builtin_amdgcn_s_barrier()
; #define PG8_SCHED __builtin_amdgcn_sched_barrier(0)
; template <class Epi, bool ALIGN_EPI>
; __device__ __forceinline__ void gemm_phase(LAS unsigned char* lds, const Gemm g, const StaticOrder& S, const Epi& E, const int tid) {
;     ...
;             PG8_WAIT_V(8); PG8_WAIT_L(0); PG8_BAR; PG8_MMA(0, 0, At, B0); PG8_MMA(0, 1, At, B1); PG8_BAR; PG8_SCHED;
;             PG8_LDA(At, 1, 1); PG8_STAGE(PG8_SB(1, 0), b3, voffB); PG8_STAGE(PG8_SB(1, 1), b3 + hstepB, voffB); PG8_STAGE(PG8_SA(1, 0), a3, voffA);
;             PG8_WAIT_V(8); PG8_WAIT_L(0); PG8_BAR; PG8_MMA(1, 0, At, B0); PG8_MMA(1, 1, At, B1); PG8_BAR; PG8_SCHED;
	s_barrier
	s_add_u32 s42, s34, 0x8000
	s_addc_u32 s43, s35, 0
	s_add_i32 s87, s87, s56
	s_mov_b32 m0, s87
	ds_read_b128 v[180:183], v155 offset:49152
	ds_read_b128 v[184:187], v155 offset:50176
	ds_read_b128 v[188:191], v155 offset:51200
	ds_read_b128 v[192:195], v155 offset:52224
	ds_read_b128 v[196:199], v155 offset:53248
	ds_read_b128 v[214:217], v155 offset:54272
	ds_read_b128 v[218:221], v155 offset:55296
	ds_read_b128 v[222:225], v155 offset:56320
	global_load_lds_dwordx4 v140, s[42:43]
	s_add_i32 m0, s87, 0x2000
	s_add_u32 s34, s34, 0xc000
	s_addc_u32 s35, s35, 0
	global_load_lds_dwordx4 v136, s[42:43]
	s_add_i32 s42, s88, s56
	s_mov_b32 m0, s42
	s_nop 0
	global_load_lds_dwordx4 v140, s[34:35]
	s_add_i32 m0, s42, 0x2000
	s_nop 0
	global_load_lds_dwordx4 v136, s[34:35]
	s_mov_b32 m0, s76
	s_nop 0
	global_load_lds_dwordx4 v142, s[22:23]
	s_mov_b32 m0, s77
	s_nop 0
	global_load_lds_dwordx4 v138, s[22:23]
	s_waitcnt vmcnt(8) lgkmcnt(0)
	s_barrier


; #define PG8_MMA(ai, bj, At, Bt) do { __builtin_amdgcn_s_setprio(1); _Pragma("unroll") for (int m = 0; m < 4; ++m) _Pragma("unroll") for (int n = 0; n < 2; ++n) _Pragma("unroll") for (int k = 0; k < 2; ++k) \
;         acc[ai][bj][m][n] = __builtin_amdgcn_mfma_f32_16x16x32_bf16(Bt[n][k], At[m][k], acc[ai][bj][m][n], 0, 0, 0); __builtin_amdgcn_s_setprio(0); } while (0)
; #define PG8_WAIT_V(n) asm volatile("s_waitcnt vmcnt(" #n ")" ::: "memory")
; #define PG8_WAIT_L(n) asm volatile("s_waitcnt lgkmcnt(" #n ")" ::: "memory")
; #define PG8_BAR __builtin_amdgcn_s_barrier()
; #define PG8_SCHED __builtin_amdgcn_sched_barrier(0)
; template <class Epi, bool ALIGN_EPI>
; __device__ __forceinline__ void gemm_phase(LAS unsigned char* lds, const Gemm g, const StaticOrder& S, const Epi& E, const int tid) {
;     ...
;             PG8_WAIT_V(8); PG8_WAIT_L(0); PG8_BAR; PG8_MMA(1, 0, At, B0); PG8_MMA(1, 1, At, B1); PG8_BAR; PG8_SCHED;
	v_mfma_f32_16x16x32_bf16 v[24:27], v[132:135], v[180:183], v[24:27]
	v_mfma_f32_16x16x32_bf16 v[20:23], v[156:159], v[180:183], v[20:23]
	v_mfma_f32_16x16x32_bf16 v[64:67], v[132:135], v[188:191], v[64:67]
	v_mfma_f32_16x16x32_bf16 v[72:75], v[156:159], v[188:191], v[72:75]
	v_mfma_f32_16x16x32_bf16 v[16:19], v[132:135], v[196:199], v[16:19]
	v_mfma_f32_16x16x32_bf16 v[12:15], v[156:159], v[196:199], v[12:15]
	v_mfma_f32_16x16x32_bf16 v[60:63], v[132:135], v[218:221], v[60:63]
	v_mfma_f32_16x16x32_bf16 v[68:71], v[156:159], v[218:221], v[68:71]
	v_mfma_f32_16x16x32_bf16 v[24:27], v[148:151], v[184:187], v[24:27]
	v_mfma_f32_16x16x32_bf16 v[20:23], v[160:163], v[184:187], v[20:23]
	v_mfma_f32_16x16x32_bf16 v[64:67], v[148:151], v[192:195], v[64:67]
	v_mfma_f32_16x16x32_bf16 v[72:75], v[160:163], v[192:195], v[72:75]
	v_mfma_f32_16x16x32_bf16 v[16:19], v[148:151], v[214:217], v[16:19]
	v_mfma_f32_16x16x32_bf16 v[12:15], v[160:163], v[214:217], v[12:15]
	v_mfma_f32_16x16x32_bf16 v[60:63], v[148:151], v[222:225], v[60:63]
	v_mfma_f32_16x16x32_bf16 v[68:71], v[160:163], v[222:225], v[68:71]


; #define PG8_MMA(ai, bj, At, Bt) do { __builtin_amdgcn_s_setprio(1); _Pragma("unroll") for (int m = 0; m < 4; ++m) _Pragma("unroll") for (int n = 0; n < 2; ++n) _Pragma("unroll") for (int k = 0; k < 2; ++k) \
;         acc[ai][bj][m][n] = __builtin_amdgcn_mfma_f32_16x16x32_bf16(Bt[n][k], At[m][k], acc[ai][bj][m][n], 0, 0, 0); __builtin_amdgcn_s_setprio(0); } while (0)
; #define PG8_WAIT_V(n) asm volatile("s_waitcnt vmcnt(" #n ")" ::: "memory")
; #define PG8_WAIT_L(n) asm volatile("s_waitcnt lgkmcnt(" #n ")" ::: "memory")
; #define PG8_BAR __builtin_amdgcn_s_barrier()
; #define PG8_SCHED __builtin_amdgcn_sched_barrier(0)
; template <class Epi, bool ALIGN_EPI>
; __device__ __forceinline__ void gemm_phase(LAS unsigned char* lds, const Gemm g, const StaticOrder& S, const Epi& E, const int tid) {
;     ...
;             PG8_WAIT_V(8); PG8_WAIT_L(0); PG8_BAR; PG8_MMA(1, 0, At, B0); PG8_MMA(1, 1, At, B1); PG8_BAR; PG8_SCHED;
	v_mfma_f32_16x16x32_bf16 v[128:131], v[164:167], v[180:183], v[128:131]
	v_mfma_f32_16x16x32_bf16 v[124:127], v[172:175], v[180:183], v[124:127]
	v_mfma_f32_16x16x32_bf16 v[120:123], v[164:167], v[188:191], v[120:123]
	v_mfma_f32_16x16x32_bf16 v[116:119], v[172:175], v[188:191], v[116:119]
	v_mfma_f32_16x16x32_bf16 v[112:115], v[164:167], v[196:199], v[112:115]
	v_mfma_f32_16x16x32_bf16 v[108:111], v[172:175], v[196:199], v[108:111]
	v_mfma_f32_16x16x32_bf16 v[104:107], v[164:167], v[218:221], v[104:107]
	v_mfma_f32_16x16x32_bf16 v[100:103], v[172:175], v[218:221], v[100:103]
	v_mfma_f32_16x16x32_bf16 v[128:131], v[168:171], v[184:187], v[128:131]
	v_mfma_f32_16x16x32_bf16 v[124:127], v[176:179], v[184:187], v[124:127]
	v_mfma_f32_16x16x32_bf16 v[120:123], v[168:171], v[192:195], v[120:123]
	v_mfma_f32_16x16x32_bf16 v[116:119], v[176:179], v[192:195], v[116:119]
	v_mfma_f32_16x16x32_bf16 v[112:115], v[168:171], v[214:217], v[112:115]
	v_mfma_f32_16x16x32_bf16 v[108:111], v[176:179], v[214:217], v[108:111]
	v_mfma_f32_16x16x32_bf16 v[104:107], v[168:171], v[222:225], v[104:107]
	v_mfma_f32_16x16x32_bf16 v[100:103], v[176:179], v[222:225], v[100:103]

; #define PG8_MMA(ai, bj, At, Bt) do { __builtin_amdgcn_s_setprio(1); _Pragma("unroll") for (int m = 0; m < 4; ++m) _Pragma("unroll") for (int n = 0; n < 2; ++n) _Pragma("unroll") for (int k = 0; k < 2; ++k) \
;         acc[ai][bj][m][n] = __builtin_amdgcn_mfma_f32_16x16x32_bf16(Bt[n][k], At[m][k], acc[ai][bj][m][n], 0, 0, 0); __builtin_amdgcn_s_setprio(0); } while (0)
; #define PG8_WAIT_V(n) asm volatile("s_waitcnt vmcnt(" #n ")" ::: "memory")
; #define PG8_WAIT_L(n) asm volatile("s_waitcnt lgkmcnt(" #n ")" ::: "memory")
; #define PG8_BAR __builtin_amdgcn_s_barrier()
; #define PG8_SCHED __builtin_amdgcn_sched_barrier(0)
; template <class Epi, bool ALIGN_EPI>
; __device__ __forceinline__ void gemm_phase(LAS unsigned char* lds, const Gemm g, const StaticOrder& S, const Epi& E, const int tid) {
;     ...
;             PG8_WAIT_V(8); PG8_WAIT_L(0); PG8_BAR; PG8_MMA(1, 0, At, B0); PG8_MMA(1, 1, At, B1); PG8_BAR; PG8_SCHED;
;         }
;         if constexpr (ALIGN_EPI) { if (wr == 0) PG8_BAR; }
	s_barrier
	s_add_i32 s86, s86, 2
	s_add_u32 s84, s84, 0x10000
	s_addc_u32 s85, s85, 0
	s_add_u32 s10, s10, 0x10000
	s_addc_u32 s11, s11, 0
	s_cmpk_gt_u32 s86, 0x55
	s_cbranch_scc0 .LBB0_294
	s_and_b64 vcc, exec, s[46:47]
	s_cbranch_vccz .LBB0_297
	s_barrier

; #define PG8_STAGE(bufoff, gbase, voff) do { _Pragma("unroll") for (int _i = 0; _i < 2; ++_i) \
;         __builtin_amdgcn_global_load_lds((const unsigned*)((const char*)(gbase) + (voff)[_i]), (LAS unsigned*)(lds + (bufoff) + ldsw + _i * 8192), 16, 0, 0); } while (0)
; #define PG8_LDA(dst, b, h) do { _Pragma("unroll") for (int m = 0; m < 4; ++m) _Pragma("unroll") for (int k = 0; k < 2; ++k) dst[m][k] = *(const LAS bf16x8*)(lds + PG8_SA(b, h) + aoff + m * 2048 + k * 1024); } while (0)
; #define PG8_LDB(dst, b, h) do { _Pragma("unroll") for (int n = 0; n < 2; ++n) _Pragma("unroll") for (int k = 0; k < 2; ++k) dst[n][k] = *(const LAS bf16x8*)(lds + PG8_SB(b, h) + boff + n * 2048 + k * 1024); } while (0)
; #define PG8_MMA(ai, bj, At, Bt) do { __builtin_amdgcn_s_setprio(1); _Pragma("unroll") for (int m = 0; m < 4; ++m) _Pragma("unroll") for (int n = 0; n < 2; ++n) _Pragma("unroll") for (int k = 0; k < 2; ++k) \
;         acc[ai][bj][m][n] = __builtin_amdgcn_mfma_f32_16x16x32_bf16(Bt[n][k], At[m][k], acc[ai][bj][m][n], 0, 0, 0); __builtin_amdgcn_s_setprio(0); } while (0)
; #define PG8_WAIT_V(n) asm volatile("s_waitcnt vmcnt(" #n ")" ::: "memory")
; #define PG8_WAIT_L(n) asm volatile("s_waitcnt lgkmcnt(" #n ")" ::: "memory")
; #define PG8_BAR __builtin_amdgcn_s_barrier()
; #define PG8_SCHED __builtin_amdgcn_sched_barrier(0)
; template <class Epi, bool ALIGN_EPI>
; __device__ __forceinline__ void gemm_phase(LAS unsigned char* lds, const Gemm g, const StaticOrder& S, const Epi& E, const int tid) {
;     ...
;         for (int t = 0; t < nt; t += 2) {
;             const bool last = (t == nt - 2);
;             const char* a1 = cA + (size_t)(t + 1) * kstepA;
;             const char* a2 = last ? nA : cA + (size_t)(t + 2) * kstepA; const char* b2 = last ? nB : cB + (size_t)(t + 2) * kstepB;
;             const char* a3 = a2 + kstepA; const char* b3 = b2 + kstepB;
;             PG8_LDB(B0, 0, 0); PG8_LDB(B1, 0, 1); PG8_SCHED; PG8_LDA(At, 0, 0); PG8_STAGE(PG8_SA(1, 1), a1 + hstepA, voffA);
;             PG8_WAIT_V(8); PG8_WAIT_L(0); PG8_BAR; PG8_MMA(0, 0, At, B0); PG8_MMA(0, 1, At, B1); PG8_BAR; PG8_SCHED;
.LBB0_385:
	s_add_u32 s50, s48, 0x4000
	s_addc_u32 s51, s49, 0
	s_cmp_eq_u32 s88, 28
	s_cselect_b32 s54, s84, s50
	s_cselect_b32 s55, s43, s51
	s_cselect_b32 s52, s85, s86
	s_cselect_b32 s53, s41, s87
	s_add_u32 s50, s54, 0x8000
	s_addc_u32 s51, s55, 0
	s_add_i32 s89, 0, 0x10000
	v_add_u32_e32 v0, s89, v167
	s_add_i32 s92, 0, 0x14000
	ds_read_b128 v[132:135], v0
	ds_read_b128 v[136:139], v0 offset:1024
	ds_read_b128 v[152:155], v0 offset:2048
	ds_read_b128 v[156:159], v0 offset:3072
	v_add_u32_e32 v0, s92, v167
	ds_read_b128 v[160:163], v0
	ds_read_b128 v[172:175], v0 offset:1024
	ds_read_b128 v[176:179], v0 offset:2048
	ds_read_b128 v[180:183], v0 offset:3072
	s_add_i32 m0, s71, 0xc000
	ds_read_b128 v[184:187], v171
	ds_read_b128 v[188:191], v171 offset:1024
	ds_read_b128 v[192:195], v171 offset:2048
	ds_read_b128 v[196:199], v171 offset:3072
	ds_read_b128 v[214:217], v171 offset:4096
	ds_read_b128 v[218:221], v171 offset:5120
	ds_read_b128 v[222:225], v171 offset:6144
	ds_read_b128 v[226:229], v171 offset:7168
	global_load_lds_dwordx4 v148, s[48:49]
	s_add_i32 m0, s71, 0xe000
	s_nop 0
	global_load_lds_dwordx4 v150, s[48:49]
	s_waitcnt vmcnt(8) lgkmcnt(0)
	s_barrier


; #define PG8_MMA(ai, bj, At, Bt) do { __builtin_amdgcn_s_setprio(1); _Pragma("unroll") for (int m = 0; m < 4; ++m) _Pragma("unroll") for (int n = 0; n < 2; ++n) _Pragma("unroll") for (int k = 0; k < 2; ++k) \
;         acc[ai][bj][m][n] = __builtin_amdgcn_mfma_f32_16x16x32_bf16(Bt[n][k], At[m][k], acc[ai][bj][m][n], 0, 0, 0); __builtin_amdgcn_s_setprio(0); } while (0)
; #define PG8_WAIT_V(n) asm volatile("s_waitcnt vmcnt(" #n ")" ::: "memory")
; #define PG8_WAIT_L(n) asm volatile("s_waitcnt lgkmcnt(" #n ")" ::: "memory")
; #define PG8_BAR __builtin_amdgcn_s_barrier()
; #define PG8_SCHED __builtin_amdgcn_sched_barrier(0)
; template <class Epi, bool ALIGN_EPI>
; __device__ __forceinline__ void gemm_phase(LAS unsigned char* lds, const Gemm g, const StaticOrder& S, const Epi& E, const int tid) {
;     ...
;             PG8_WAIT_V(8); PG8_WAIT_L(0); PG8_BAR; PG8_MMA(0, 0, At, B0); PG8_MMA(0, 1, At, B1); PG8_BAR; PG8_SCHED;
	v_mfma_f32_16x16x32_bf16 v[128:131], v[132:135], v[184:187], v[128:131]
	v_mfma_f32_16x16x32_bf16 v[116:119], v[152:155], v[184:187], v[116:119]
	v_mfma_f32_16x16x32_bf16 v[124:127], v[132:135], v[192:195], v[124:127]
	v_mfma_f32_16x16x32_bf16 v[108:111], v[152:155], v[192:195], v[108:111]
	v_mfma_f32_16x16x32_bf16 v[120:123], v[132:135], v[214:217], v[120:123]
	v_mfma_f32_16x16x32_bf16 v[100:103], v[152:155], v[214:217], v[100:103]
	v_mfma_f32_16x16x32_bf16 v[112:115], v[132:135], v[222:225], v[112:115]
	v_mfma_f32_16x16x32_bf16 v[92:95], v[152:155], v[222:225], v[92:95]
	v_mfma_f32_16x16x32_bf16 v[128:131], v[136:139], v[188:191], v[128:131]
	v_mfma_f32_16x16x32_bf16 v[116:119], v[156:159], v[188:191], v[116:119]
	v_mfma_f32_16x16x32_bf16 v[124:127], v[136:139], v[196:199], v[124:127]
	v_mfma_f32_16x16x32_bf16 v[108:111], v[156:159], v[196:199], v[108:111]
	v_mfma_f32_16x16x32_bf16 v[120:123], v[136:139], v[218:221], v[120:123]
	v_mfma_f32_16x16x32_bf16 v[100:103], v[156:159], v[218:221], v[100:103]
	v_mfma_f32_16x16x32_bf16 v[112:115], v[136:139], v[226:229], v[112:115]
	v_mfma_f32_16x16x32_bf16 v[92:95], v[156:159], v[226:229], v[92:95]


; #define PG8_MMA(ai, bj, At, Bt) do { __builtin_amdgcn_s_setprio(1); _Pragma("unroll") for (int m = 0; m < 4; ++m) _Pragma("unroll") for (int n = 0; n < 2; ++n) _Pragma("unroll") for (int k = 0; k < 2; ++k) \
;         acc[ai][bj][m][n] = __builtin_amdgcn_mfma_f32_16x16x32_bf16(Bt[n][k], At[m][k], acc[ai][bj][m][n], 0, 0, 0); __builtin_amdgcn_s_setprio(0); } while (0)
; #define PG8_WAIT_V(n) asm volatile("s_waitcnt vmcnt(" #n ")" ::: "memory")
; #define PG8_WAIT_L(n) asm volatile("s_waitcnt lgkmcnt(" #n ")" ::: "memory")
; #define PG8_BAR __builtin_amdgcn_s_barrier()
; #define PG8_SCHED __builtin_amdgcn_sched_barrier(0)
; template <class Epi, bool ALIGN_EPI>
; __device__ __forceinline__ void gemm_phase(LAS unsigned char* lds, const Gemm g, const StaticOrder& S, const Epi& E, const int tid) {
;     ...
;             PG8_WAIT_V(8); PG8_WAIT_L(0); PG8_BAR; PG8_MMA(0, 0, At, B0); PG8_MMA(0, 1, At, B1); PG8_BAR; PG8_SCHED;
	v_mfma_f32_16x16x32_bf16 v[104:107], v[160:163], v[184:187], v[104:107]
	v_mfma_f32_16x16x32_bf16 v[80:83], v[176:179], v[184:187], v[80:83]
	v_mfma_f32_16x16x32_bf16 v[96:99], v[160:163], v[192:195], v[96:99]
	v_mfma_f32_16x16x32_bf16 v[68:71], v[176:179], v[192:195], v[68:71]
	v_mfma_f32_16x16x32_bf16 v[88:91], v[160:163], v[214:217], v[88:91]
	v_mfma_f32_16x16x32_bf16 v[60:63], v[176:179], v[214:217], v[60:63]
	v_mfma_f32_16x16x32_bf16 v[76:79], v[160:163], v[222:225], v[76:79]
	v_mfma_f32_16x16x32_bf16 v[48:51], v[176:179], v[222:225], v[48:51]
	v_mfma_f32_16x16x32_bf16 v[104:107], v[172:175], v[188:191], v[104:107]
	v_mfma_f32_16x16x32_bf16 v[80:83], v[180:183], v[188:191], v[80:83]
	v_mfma_f32_16x16x32_bf16 v[96:99], v[172:175], v[196:199], v[96:99]
	v_mfma_f32_16x16x32_bf16 v[68:71], v[180:183], v[196:199], v[68:71]
	v_mfma_f32_16x16x32_bf16 v[88:91], v[172:175], v[218:221], v[88:91]
	v_mfma_f32_16x16x32_bf16 v[60:63], v[180:183], v[218:221], v[60:63]
	v_mfma_f32_16x16x32_bf16 v[76:79], v[172:175], v[226:229], v[76:79]
	v_mfma_f32_16x16x32_bf16 v[48:51], v[180:183], v[226:229], v[48:51]

; #define PG8_STAGE(bufoff, gbase, voff) do { _Pragma("unroll") for (int _i = 0; _i < 2; ++_i) \
;         __builtin_amdgcn_global_load_lds((const unsigned*)((const char*)(gbase) + (voff)[_i]), (LAS unsigned*)(lds + (bufoff) + ldsw + _i * 8192), 16, 0, 0); } while (0)
; #define PG8_LDA(dst, b, h) do { _Pragma("unroll") for (int m = 0; m < 4; ++m) _Pragma("unroll") for (int k = 0; k < 2; ++k) dst[m][k] = *(const LAS bf16x8*)(lds + PG8_SA(b, h) + aoff + m * 2048 + k * 1024); } while (0)
; #define PG8_MMA(ai, bj, At, Bt) do { __builtin_amdgcn_s_setprio(1); _Pragma("unroll") for (int m = 0; m < 4; ++m) _Pragma("unroll") for (int n = 0; n < 2; ++n) _Pragma("unroll") for (int k = 0; k < 2; ++k) \
;         acc[ai][bj][m][n] = __builtin_amdgcn_mfma_f32_16x16x32_bf16(Bt[n][k], At[m][k], acc[ai][bj][m][n], 0, 0, 0); __builtin_amdgcn_s_setprio(0); } while (0)
; #define PG8_WAIT_V(n) asm volatile("s_waitcnt vmcnt(" #n ")" ::: "memory")
; #define PG8_WAIT_L(n) asm volatile("s_waitcnt lgkmcnt(" #n ")" ::: "memory")
; #define PG8_BAR __builtin_amdgcn_s_barrier()
; #define PG8_SCHED __builtin_amdgcn_sched_barrier(0)
; template <class Epi, bool ALIGN_EPI>
; __device__ __forceinline__ void gemm_phase(LAS unsigned char* lds, const Gemm g, const StaticOrder& S, const Epi& E, const int tid) {
;     ...
;             PG8_WAIT_V(8); PG8_WAIT_L(0); PG8_BAR; PG8_MMA(0, 0, At, B0); PG8_MMA(0, 1, At, B1); PG8_BAR; PG8_SCHED;
;             PG8_LDA(At, 0, 1); PG8_STAGE(PG8_SB(0, 0), b2, voffB); PG8_STAGE(PG8_SB(0, 1), b2 + hstepB, voffB); PG8_STAGE(PG8_SA(0, 0), a2, voffA);
;             PG8_WAIT_V(8); PG8_WAIT_L(0); PG8_BAR; PG8_MMA(1, 0, At, B0); PG8_MMA(1, 1, At, B1); PG8_BAR; PG8_SCHED;
	s_barrier
	s_add_i32 s89, s89, s61
	s_mov_b32 m0, s89
	ds_read_b128 v[184:187], v171 offset:16384
	ds_read_b128 v[188:191], v171 offset:17408
	ds_read_b128 v[192:195], v171 offset:18432
	ds_read_b128 v[196:199], v171 offset:19456
	ds_read_b128 v[214:217], v171 offset:20480
	ds_read_b128 v[218:221], v171 offset:21504
	ds_read_b128 v[222:225], v171 offset:22528
	ds_read_b128 v[226:229], v171 offset:23552
	global_load_lds_dwordx4 v144, s[52:53]
	s_add_i32 m0, s89, 0x2000
	s_add_u32 s90, s52, 0x4000
	s_addc_u32 s91, s53, 0
	s_add_i32 s89, s92, s61
	global_load_lds_dwordx4 v140, s[52:53]
	s_mov_b32 m0, s89
	s_nop 0
	global_load_lds_dwordx4 v144, s[90:91]
	s_add_i32 m0, s89, 0x2000
	s_nop 0
	global_load_lds_dwordx4 v140, s[90:91]
	s_mov_b32 m0, s71
	s_nop 0
	global_load_lds_dwordx4 v146, s[54:55]
	s_mov_b32 m0, s72
	s_nop 0
	global_load_lds_dwordx4 v142, s[54:55]
	s_waitcnt vmcnt(8) lgkmcnt(0)
	s_barrier


; #define PG8_MMA(ai, bj, At, Bt) do { __builtin_amdgcn_s_setprio(1); _Pragma("unroll") for (int m = 0; m < 4; ++m) _Pragma("unroll") for (int n = 0; n < 2; ++n) _Pragma("unroll") for (int k = 0; k < 2; ++k) \
;         acc[ai][bj][m][n] = __builtin_amdgcn_mfma_f32_16x16x32_bf16(Bt[n][k], At[m][k], acc[ai][bj][m][n], 0, 0, 0); __builtin_amdgcn_s_setprio(0); } while (0)
; #define PG8_WAIT_V(n) asm volatile("s_waitcnt vmcnt(" #n ")" ::: "memory")
; #define PG8_WAIT_L(n) asm volatile("s_waitcnt lgkmcnt(" #n ")" ::: "memory")
; #define PG8_BAR __builtin_amdgcn_s_barrier()
; #define PG8_SCHED __builtin_amdgcn_sched_barrier(0)
; template <class Epi, bool ALIGN_EPI>
; __device__ __forceinline__ void gemm_phase(LAS unsigned char* lds, const Gemm g, const StaticOrder& S, const Epi& E, const int tid) {
;     ...
;             PG8_WAIT_V(8); PG8_WAIT_L(0); PG8_BAR; PG8_MMA(1, 0, At, B0); PG8_MMA(1, 1, At, B1); PG8_BAR; PG8_SCHED;
	v_mfma_f32_16x16x32_bf16 v[84:87], v[132:135], v[184:187], v[84:87]
	v_mfma_f32_16x16x32_bf16 v[56:59], v[152:155], v[184:187], v[56:59]
	v_mfma_f32_16x16x32_bf16 v[72:75], v[132:135], v[192:195], v[72:75]
	v_mfma_f32_16x16x32_bf16 v[44:47], v[152:155], v[192:195], v[44:47]
	v_mfma_f32_16x16x32_bf16 v[64:67], v[132:135], v[214:217], v[64:67]
	v_mfma_f32_16x16x32_bf16 v[36:39], v[152:155], v[214:217], v[36:39]
	v_mfma_f32_16x16x32_bf16 v[52:55], v[132:135], v[222:225], v[52:55]
	v_mfma_f32_16x16x32_bf16 v[28:31], v[152:155], v[222:225], v[28:31]
	v_mfma_f32_16x16x32_bf16 v[84:87], v[136:139], v[188:191], v[84:87]
	v_mfma_f32_16x16x32_bf16 v[56:59], v[156:159], v[188:191], v[56:59]
	v_mfma_f32_16x16x32_bf16 v[72:75], v[136:139], v[196:199], v[72:75]
	v_mfma_f32_16x16x32_bf16 v[44:47], v[156:159], v[196:199], v[44:47]
	v_mfma_f32_16x16x32_bf16 v[64:67], v[136:139], v[218:221], v[64:67]
	v_mfma_f32_16x16x32_bf16 v[36:39], v[156:159], v[218:221], v[36:39]
	v_mfma_f32_16x16x32_bf16 v[52:55], v[136:139], v[226:229], v[52:55]
	v_mfma_f32_16x16x32_bf16 v[28:31], v[156:159], v[226:229], v[28:31]


; #define PG8_MMA(ai, bj, At, Bt) do { __builtin_amdgcn_s_setprio(1); _Pragma("unroll") for (int m = 0; m < 4; ++m) _Pragma("unroll") for (int n = 0; n < 2; ++n) _Pragma("unroll") for (int k = 0; k < 2; ++k) \
;         acc[ai][bj][m][n] = __builtin_amdgcn_mfma_f32_16x16x32_bf16(Bt[n][k], At[m][k], acc[ai][bj][m][n], 0, 0, 0); __builtin_amdgcn_s_setprio(0); } while (0)
; #define PG8_WAIT_V(n) asm volatile("s_waitcnt vmcnt(" #n ")" ::: "memory")
; #define PG8_WAIT_L(n) asm volatile("s_waitcnt lgkmcnt(" #n ")" ::: "memory")
; #define PG8_BAR __builtin_amdgcn_s_barrier()
; #define PG8_SCHED __builtin_amdgcn_sched_barrier(0)
; template <class Epi, bool ALIGN_EPI>
; __device__ __forceinline__ void gemm_phase(LAS unsigned char* lds, const Gemm g, const StaticOrder& S, const Epi& E, const int tid) {
;     ...
;             PG8_WAIT_V(8); PG8_WAIT_L(0); PG8_BAR; PG8_MMA(1, 0, At, B0); PG8_MMA(1, 1, At, B1); PG8_BAR; PG8_SCHED;
	v_mfma_f32_16x16x32_bf16 v[40:43], v[160:163], v[184:187], v[40:43]
	v_mfma_f32_16x16x32_bf16 v[20:23], v[176:179], v[184:187], v[20:23]
	v_mfma_f32_16x16x32_bf16 v[32:35], v[160:163], v[192:195], v[32:35]
	v_mfma_f32_16x16x32_bf16 v[12:15], v[176:179], v[192:195], v[12:15]
	v_mfma_f32_16x16x32_bf16 v[24:27], v[160:163], v[214:217], v[24:27]
	v_mfma_f32_16x16x32_bf16 v[8:11], v[176:179], v[214:217], v[8:11]
	v_mfma_f32_16x16x32_bf16 v[16:19], v[160:163], v[222:225], v[16:19]
	v_mfma_f32_16x16x32_bf16 v[2:5], v[176:179], v[222:225], v[4:7]
	v_mfma_f32_16x16x32_bf16 v[40:43], v[172:175], v[188:191], v[40:43]
	v_mfma_f32_16x16x32_bf16 v[20:23], v[180:183], v[188:191], v[20:23]
	v_mfma_f32_16x16x32_bf16 v[32:35], v[172:175], v[196:199], v[32:35]
	v_mfma_f32_16x16x32_bf16 v[12:15], v[180:183], v[196:199], v[12:15]
	v_mfma_f32_16x16x32_bf16 v[24:27], v[172:175], v[218:221], v[24:27]
	v_mfma_f32_16x16x32_bf16 v[8:11], v[180:183], v[218:221], v[8:11]
	v_mfma_f32_16x16x32_bf16 v[16:19], v[172:175], v[226:229], v[16:19]
	v_mfma_f32_16x16x32_bf16 v[2:5], v[180:183], v[226:229], v[2:5]

; #define PG8_STAGE(bufoff, gbase, voff) do { _Pragma("unroll") for (int _i = 0; _i < 2; ++_i) \
;         __builtin_amdgcn_global_load_lds((const unsigned*)((const char*)(gbase) + (voff)[_i]), (LAS unsigned*)(lds + (bufoff) + ldsw + _i * 8192), 16, 0, 0); } while (0)
; #define PG8_LDA(dst, b, h) do { _Pragma("unroll") for (int m = 0; m < 4; ++m) _Pragma("unroll") for (int k = 0; k < 2; ++k) dst[m][k] = *(const LAS bf16x8*)(lds + PG8_SA(b, h) + aoff + m * 2048 + k * 1024); } while (0)
; #define PG8_LDB(dst, b, h) do { _Pragma("unroll") for (int n = 0; n < 2; ++n) _Pragma("unroll") for (int k = 0; k < 2; ++k) dst[n][k] = *(const LAS bf16x8*)(lds + PG8_SB(b, h) + boff + n * 2048 + k * 1024); } while (0)
; #define PG8_MMA(ai, bj, At, Bt) do { __builtin_amdgcn_s_setprio(1); _Pragma("unroll") for (int m = 0; m < 4; ++m) _Pragma("unroll") for (int n = 0; n < 2; ++n) _Pragma("unroll") for (int k = 0; k < 2; ++k) \
;         acc[ai][bj][m][n] = __builtin_amdgcn_mfma_f32_16x16x32_bf16(Bt[n][k], At[m][k], acc[ai][bj][m][n], 0, 0, 0); __builtin_amdgcn_s_setprio(0); } while (0)
; #define PG8_WAIT_V(n) asm volatile("s_waitcnt vmcnt(" #n ")" ::: "memory")
; #define PG8_WAIT_L(n) asm volatile("s_waitcnt lgkmcnt(" #n ")" ::: "memory")
; #define PG8_BAR __builtin_amdgcn_s_barrier()
; #define PG8_SCHED __builtin_amdgcn_sched_barrier(0)
; template <class Epi, bool ALIGN_EPI>
; __device__ __forceinline__ void gemm_phase(LAS unsigned char* lds, const Gemm g, const StaticOrder& S, const Epi& E, const int tid) {
;     ...
;             PG8_WAIT_V(8); PG8_WAIT_L(0); PG8_BAR; PG8_MMA(1, 0, At, B0); PG8_MMA(1, 1, At, B1); PG8_BAR; PG8_SCHED;
;             PG8_LDB(B0, 1, 0); PG8_LDB(B1, 1, 1); PG8_SCHED; PG8_LDA(At, 1, 0); PG8_STAGE(PG8_SA(0, 1), a2 + hstepA, voffA);
;             PG8_WAIT_V(8); PG8_WAIT_L(0); PG8_BAR; PG8_MMA(0, 0, At, B0); PG8_MMA(0, 1, At, B1); PG8_BAR; PG8_SCHED;
	s_barrier
	s_add_i32 s89, 0, 0x18000
	v_add_u32_e32 v0, s89, v167
	s_add_i32 s90, 0, 0x1c000
	ds_read_b128 v[132:135], v0
	ds_read_b128 v[136:139], v0 offset:1024
	ds_read_b128 v[152:155], v0 offset:2048
	ds_read_b128 v[156:159], v0 offset:3072
	v_add_u32_e32 v0, s90, v167
	ds_read_b128 v[160:163], v0
	ds_read_b128 v[172:175], v0 offset:1024
	ds_read_b128 v[176:179], v0 offset:2048
	ds_read_b128 v[180:183], v0 offset:3072
	s_add_u32 s54, s54, 0x4000
	s_addc_u32 s55, s55, 0
	s_mov_b32 m0, s73
	ds_read_b128 v[184:187], v171 offset:32768
	ds_read_b128 v[188:191], v171 offset:33792
	ds_read_b128 v[192:195], v171 offset:34816
	ds_read_b128 v[196:199], v171 offset:35840
	ds_read_b128 v[214:217], v171 offset:36864
	ds_read_b128 v[218:221], v171 offset:37888
	ds_read_b128 v[222:225], v171 offset:38912
	ds_read_b128 v[226:229], v171 offset:39936
	global_load_lds_dwordx4 v146, s[54:55]
	s_mov_b32 m0, s74
	s_nop 0
	global_load_lds_dwordx4 v142, s[54:55]
	s_waitcnt vmcnt(8) lgkmcnt(0)
	s_barrier


; #define PG8_MMA(ai, bj, At, Bt) do { __builtin_amdgcn_s_setprio(1); _Pragma("unroll") for (int m = 0; m < 4; ++m) _Pragma("unroll") for (int n = 0; n < 2; ++n) _Pragma("unroll") for (int k = 0; k < 2; ++k) \
;         acc[ai][bj][m][n] = __builtin_amdgcn_mfma_f32_16x16x32_bf16(Bt[n][k], At[m][k], acc[ai][bj][m][n], 0, 0, 0); __builtin_amdgcn_s_setprio(0); } while (0)
; #define PG8_WAIT_V(n) asm volatile("s_waitcnt vmcnt(" #n ")" ::: "memory")
; #define PG8_WAIT_L(n) asm volatile("s_waitcnt lgkmcnt(" #n ")" ::: "memory")
; #define PG8_BAR __builtin_amdgcn_s_barrier()
; #define PG8_SCHED __builtin_amdgcn_sched_barrier(0)
; template <class Epi, bool ALIGN_EPI>
; __device__ __forceinline__ void gemm_phase(LAS unsigned char* lds, const Gemm g, const StaticOrder& S, const Epi& E, const int tid) {
;     ...
;             PG8_WAIT_V(8); PG8_WAIT_L(0); PG8_BAR; PG8_MMA(0, 0, At, B0); PG8_MMA(0, 1, At, B1); PG8_BAR; PG8_SCHED;
	v_mfma_f32_16x16x32_bf16 v[128:131], v[132:135], v[184:187], v[128:131]
	v_mfma_f32_16x16x32_bf16 v[116:119], v[152:155], v[184:187], v[116:119]
	v_mfma_f32_16x16x32_bf16 v[124:127], v[132:135], v[192:195], v[124:127]
	v_mfma_f32_16x16x32_bf16 v[108:111], v[152:155], v[192:195], v[108:111]
	v_mfma_f32_16x16x32_bf16 v[120:123], v[132:135], v[214:217], v[120:123]
	v_mfma_f32_16x16x32_bf16 v[100:103], v[152:155], v[214:217], v[100:103]
	v_mfma_f32_16x16x32_bf16 v[112:115], v[132:135], v[222:225], v[112:115]
	v_mfma_f32_16x16x32_bf16 v[92:95], v[152:155], v[222:225], v[92:95]
	v_mfma_f32_16x16x32_bf16 v[128:131], v[136:139], v[188:191], v[128:131]
	v_mfma_f32_16x16x32_bf16 v[116:119], v[156:159], v[188:191], v[116:119]
	v_mfma_f32_16x16x32_bf16 v[124:127], v[136:139], v[196:199], v[124:127]
	v_mfma_f32_16x16x32_bf16 v[108:111], v[156:159], v[196:199], v[108:111]
	v_mfma_f32_16x16x32_bf16 v[120:123], v[136:139], v[218:221], v[120:123]
	v_mfma_f32_16x16x32_bf16 v[100:103], v[156:159], v[218:221], v[100:103]
	v_mfma_f32_16x16x32_bf16 v[112:115], v[136:139], v[226:229], v[112:115]
	v_mfma_f32_16x16x32_bf16 v[92:95], v[156:159], v[226:229], v[92:95]


; #define PG8_MMA(ai, bj, At, Bt) do { __builtin_amdgcn_s_setprio(1); _Pragma("unroll") for (int m = 0; m < 4; ++m) _Pragma("unroll") for (int n = 0; n < 2; ++n) _Pragma("unroll") for (int k = 0; k < 2; ++k) \
;         acc[ai][bj][m][n] = __builtin_amdgcn_mfma_f32_16x16x32_bf16(Bt[n][k], At[m][k], acc[ai][bj][m][n], 0, 0, 0); __builtin_amdgcn_s_setprio(0); } while (0)
; #define PG8_WAIT_V(n) asm volatile("s_waitcnt vmcnt(" #n ")" ::: "memory")
; #define PG8_WAIT_L(n) asm volatile("s_waitcnt lgkmcnt(" #n ")" ::: "memory")
; #define PG8_BAR __builtin_amdgcn_s_barrier()
; #define PG8_SCHED __builtin_amdgcn_sched_barrier(0)
; template <class Epi, bool ALIGN_EPI>
; __device__ __forceinline__ void gemm_phase(LAS unsigned char* lds, const Gemm g, const StaticOrder& S, const Epi& E, const int tid) {
;     ...
;             PG8_WAIT_V(8); PG8_WAIT_L(0); PG8_BAR; PG8_MMA(0, 0, At, B0); PG8_MMA(0, 1, At, B1); PG8_BAR; PG8_SCHED;
	v_mfma_f32_16x16x32_bf16 v[104:107], v[160:163], v[184:187], v[104:107]
	v_mfma_f32_16x16x32_bf16 v[80:83], v[176:179], v[184:187], v[80:83]
	v_mfma_f32_16x16x32_bf16 v[96:99], v[160:163], v[192:195], v[96:99]
	v_mfma_f32_16x16x32_bf16 v[68:71], v[176:179], v[192:195], v[68:71]
	v_mfma_f32_16x16x32_bf16 v[88:91], v[160:163], v[214:217], v[88:91]
	v_mfma_f32_16x16x32_bf16 v[60:63], v[176:179], v[214:217], v[60:63]
	v_mfma_f32_16x16x32_bf16 v[76:79], v[160:163], v[222:225], v[76:79]
	v_mfma_f32_16x16x32_bf16 v[48:51], v[176:179], v[222:225], v[48:51]
	v_mfma_f32_16x16x32_bf16 v[104:107], v[172:175], v[188:191], v[104:107]
	v_mfma_f32_16x16x32_bf16 v[80:83], v[180:183], v[188:191], v[80:83]
	v_mfma_f32_16x16x32_bf16 v[96:99], v[172:175], v[196:199], v[96:99]
	v_mfma_f32_16x16x32_bf16 v[68:71], v[180:183], v[196:199], v[68:71]
	v_mfma_f32_16x16x32_bf16 v[88:91], v[172:175], v[218:221], v[88:91]
	v_mfma_f32_16x16x32_bf16 v[60:63], v[180:183], v[218:221], v[60:63]
	v_mfma_f32_16x16x32_bf16 v[76:79], v[172:175], v[226:229], v[76:79]
	v_mfma_f32_16x16x32_bf16 v[48:51], v[180:183], v[226:229], v[48:51]

; #define PG8_STAGE(bufoff, gbase, voff) do { _Pragma("unroll") for (int _i = 0; _i < 2; ++_i) \
;         __builtin_amdgcn_global_load_lds((const unsigned*)((const char*)(gbase) + (voff)[_i]), (LAS unsigned*)(lds + (bufoff) + ldsw + _i * 8192), 16, 0, 0); } while (0)
; #define PG8_LDA(dst, b, h) do { _Pragma("unroll") for (int m = 0; m < 4; ++m) _Pragma("unroll") for (int k = 0; k < 2; ++k) dst[m][k] = *(const LAS bf16x8*)(lds + PG8_SA(b, h) + aoff + m * 2048 + k * 1024); } while (0)
; #define PG8_MMA(ai, bj, At, Bt) do { __builtin_amdgcn_s_setprio(1); _Pragma("unroll") for (int m = 0; m < 4; ++m) _Pragma("unroll") for (int n = 0; n < 2; ++n) _Pragma("unroll") for (int k = 0; k < 2; ++k) \
;         acc[ai][bj][m][n] = __builtin_amdgcn_mfma_f32_16x16x32_bf16(Bt[n][k], At[m][k], acc[ai][bj][m][n], 0, 0, 0); __builtin_amdgcn_s_setprio(0); } while (0)
; #define PG8_WAIT_V(n) asm volatile("s_waitcnt vmcnt(" #n ")" ::: "memory")
; #define PG8_WAIT_L(n) asm volatile("s_waitcnt lgkmcnt(" #n ")" ::: "memory")
; #define PG8_BAR __builtin_amdgcn_s_barrier()
; #define PG8_SCHED __builtin_amdgcn_sched_barrier(0)
; template <class Epi, bool ALIGN_EPI>
; __device__ __forceinline__ void gemm_phase(LAS unsigned char* lds, const Gemm g, const StaticOrder& S, const Epi& E, const int tid) {
;     ...
;             PG8_WAIT_V(8); PG8_WAIT_L(0); PG8_BAR; PG8_MMA(0, 0, At, B0); PG8_MMA(0, 1, At, B1); PG8_BAR; PG8_SCHED;
;             PG8_LDA(At, 1, 1); PG8_STAGE(PG8_SB(1, 0), b3, voffB); PG8_STAGE(PG8_SB(1, 1), b3 + hstepB, voffB); PG8_STAGE(PG8_SA(1, 0), a3, voffA);
;             PG8_WAIT_V(8); PG8_WAIT_L(0); PG8_BAR; PG8_MMA(1, 0, At, B0); PG8_MMA(1, 1, At, B1); PG8_BAR; PG8_SCHED;
	s_barrier
	s_add_u32 s54, s52, 0x8000
	s_addc_u32 s55, s53, 0
	s_add_i32 s89, s89, s61
	s_mov_b32 m0, s89
	ds_read_b128 v[184:187], v171 offset:49152
	ds_read_b128 v[188:191], v171 offset:50176
	ds_read_b128 v[192:195], v171 offset:51200
	ds_read_b128 v[196:199], v171 offset:52224
	ds_read_b128 v[214:217], v171 offset:53248
	ds_read_b128 v[218:221], v171 offset:54272
	ds_read_b128 v[222:225], v171 offset:55296
	ds_read_b128 v[226:229], v171 offset:56320
	global_load_lds_dwordx4 v144, s[54:55]
	s_add_i32 m0, s89, 0x2000
	s_add_u32 s52, s52, 0xc000
	s_addc_u32 s53, s53, 0
	global_load_lds_dwordx4 v140, s[54:55]
	s_add_i32 s54, s90, s61
	s_mov_b32 m0, s54
	s_nop 0
	global_load_lds_dwordx4 v144, s[52:53]
	s_add_i32 m0, s54, 0x2000
	s_nop 0
	global_load_lds_dwordx4 v140, s[52:53]
	s_mov_b32 m0, s77
	s_nop 0
	global_load_lds_dwordx4 v146, s[50:51]
	s_mov_b32 m0, s78
	s_nop 0
	global_load_lds_dwordx4 v142, s[50:51]
	s_waitcnt vmcnt(8) lgkmcnt(0)
	s_barrier


; #define PG8_MMA(ai, bj, At, Bt) do { __builtin_amdgcn_s_setprio(1); _Pragma("unroll") for (int m = 0; m < 4; ++m) _Pragma("unroll") for (int n = 0; n < 2; ++n) _Pragma("unroll") for (int k = 0; k < 2; ++k) \
;         acc[ai][bj][m][n] = __builtin_amdgcn_mfma_f32_16x16x32_bf16(Bt[n][k], At[m][k], acc[ai][bj][m][n], 0, 0, 0); __builtin_amdgcn_s_setprio(0); } while (0)
; #define PG8_WAIT_V(n) asm volatile("s_waitcnt vmcnt(" #n ")" ::: "memory")
; #define PG8_WAIT_L(n) asm volatile("s_waitcnt lgkmcnt(" #n ")" ::: "memory")
; #define PG8_BAR __builtin_amdgcn_s_barrier()
; #define PG8_SCHED __builtin_amdgcn_sched_barrier(0)
; template <class Epi, bool ALIGN_EPI>
; __device__ __forceinline__ void gemm_phase(LAS unsigned char* lds, const Gemm g, const StaticOrder& S, const Epi& E, const int tid) {
;     ...
;             PG8_WAIT_V(8); PG8_WAIT_L(0); PG8_BAR; PG8_MMA(1, 0, At, B0); PG8_MMA(1, 1, At, B1); PG8_BAR; PG8_SCHED;
	v_mfma_f32_16x16x32_bf16 v[84:87], v[132:135], v[184:187], v[84:87]
	v_mfma_f32_16x16x32_bf16 v[56:59], v[152:155], v[184:187], v[56:59]
	v_mfma_f32_16x16x32_bf16 v[72:75], v[132:135], v[192:195], v[72:75]
	v_mfma_f32_16x16x32_bf16 v[44:47], v[152:155], v[192:195], v[44:47]
	v_mfma_f32_16x16x32_bf16 v[64:67], v[132:135], v[214:217], v[64:67]
	v_mfma_f32_16x16x32_bf16 v[36:39], v[152:155], v[214:217], v[36:39]
	v_mfma_f32_16x16x32_bf16 v[52:55], v[132:135], v[222:225], v[52:55]
	v_mfma_f32_16x16x32_bf16 v[28:31], v[152:155], v[222:225], v[28:31]
	v_mfma_f32_16x16x32_bf16 v[84:87], v[136:139], v[188:191], v[84:87]
	v_mfma_f32_16x16x32_bf16 v[56:59], v[156:159], v[188:191], v[56:59]
	v_mfma_f32_16x16x32_bf16 v[72:75], v[136:139], v[196:199], v[72:75]
	v_mfma_f32_16x16x32_bf16 v[44:47], v[156:159], v[196:199], v[44:47]
	v_mfma_f32_16x16x32_bf16 v[64:67], v[136:139], v[218:221], v[64:67]
	v_mfma_f32_16x16x32_bf16 v[36:39], v[156:159], v[218:221], v[36:39]
	v_mfma_f32_16x16x32_bf16 v[52:55], v[136:139], v[226:229], v[52:55]
	v_mfma_f32_16x16x32_bf16 v[28:31], v[156:159], v[226:229], v[28:31]


; #define PG8_MMA(ai, bj, At, Bt) do { __builtin_amdgcn_s_setprio(1); _Pragma("unroll") for (int m = 0; m < 4; ++m) _Pragma("unroll") for (int n = 0; n < 2; ++n) _Pragma("unroll") for (int k = 0; k < 2; ++k) \
;         acc[ai][bj][m][n] = __builtin_amdgcn_mfma_f32_16x16x32_bf16(Bt[n][k], At[m][k], acc[ai][bj][m][n], 0, 0, 0); __builtin_amdgcn_s_setprio(0); } while (0)
; #define PG8_WAIT_V(n) asm volatile("s_waitcnt vmcnt(" #n ")" ::: "memory")
; #define PG8_WAIT_L(n) asm volatile("s_waitcnt lgkmcnt(" #n ")" ::: "memory")
; #define PG8_BAR __builtin_amdgcn_s_barrier()
; #define PG8_SCHED __builtin_amdgcn_sched_barrier(0)
; template <class Epi, bool ALIGN_EPI>
; __device__ __forceinline__ void gemm_phase(LAS unsigned char* lds, const Gemm g, const StaticOrder& S, const Epi& E, const int tid) {
;     ...
;             PG8_WAIT_V(8); PG8_WAIT_L(0); PG8_BAR; PG8_MMA(1, 0, At, B0); PG8_MMA(1, 1, At, B1); PG8_BAR; PG8_SCHED;
	v_mfma_f32_16x16x32_bf16 v[40:43], v[160:163], v[184:187], v[40:43]
	v_mfma_f32_16x16x32_bf16 v[20:23], v[176:179], v[184:187], v[20:23]
	v_mfma_f32_16x16x32_bf16 v[32:35], v[160:163], v[192:195], v[32:35]
	v_mfma_f32_16x16x32_bf16 v[12:15], v[176:179], v[192:195], v[12:15]
	v_mfma_f32_16x16x32_bf16 v[24:27], v[160:163], v[214:217], v[24:27]
	v_mfma_f32_16x16x32_bf16 v[6:9], v[176:179], v[214:217], v[8:11]
	v_mfma_f32_16x16x32_bf16 v[16:19], v[160:163], v[222:225], v[16:19]
	v_mfma_f32_16x16x32_bf16 v[2:5], v[176:179], v[222:225], v[2:5]
	v_mfma_f32_16x16x32_bf16 v[40:43], v[172:175], v[188:191], v[40:43]
	v_mfma_f32_16x16x32_bf16 v[20:23], v[180:183], v[188:191], v[20:23]
	v_mfma_f32_16x16x32_bf16 v[32:35], v[172:175], v[196:199], v[32:35]
	v_mfma_f32_16x16x32_bf16 v[12:15], v[180:183], v[196:199], v[12:15]
	v_mfma_f32_16x16x32_bf16 v[24:27], v[172:175], v[218:221], v[24:27]
	v_mfma_f32_16x16x32_bf16 v[8:11], v[180:183], v[218:221], v[6:9]
	v_mfma_f32_16x16x32_bf16 v[16:19], v[172:175], v[226:229], v[16:19]
	v_mfma_f32_16x16x32_bf16 v[4:7], v[180:183], v[226:229], v[2:5]

; #define PG8_MMA(ai, bj, At, Bt) do { __builtin_amdgcn_s_setprio(1); _Pragma("unroll") for (int m = 0; m < 4; ++m) _Pragma("unroll") for (int n = 0; n < 2; ++n) _Pragma("unroll") for (int k = 0; k < 2; ++k) \
;         acc[ai][bj][m][n] = __builtin_amdgcn_mfma_f32_16x16x32_bf16(Bt[n][k], At[m][k], acc[ai][bj][m][n], 0, 0, 0); __builtin_amdgcn_s_setprio(0); } while (0)
; #define PG8_WAIT_V(n) asm volatile("s_waitcnt vmcnt(" #n ")" ::: "memory")
; #define PG8_WAIT_L(n) asm volatile("s_waitcnt lgkmcnt(" #n ")" ::: "memory")
; #define PG8_BAR __builtin_amdgcn_s_barrier()
; #define PG8_SCHED __builtin_amdgcn_sched_barrier(0)
; template <class Epi, bool ALIGN_EPI>
; __device__ __forceinline__ void gemm_phase(LAS unsigned char* lds, const Gemm g, const StaticOrder& S, const Epi& E, const int tid) {
;     ...
;             PG8_WAIT_V(8); PG8_WAIT_L(0); PG8_BAR; PG8_MMA(1, 0, At, B0); PG8_MMA(1, 1, At, B1); PG8_BAR; PG8_SCHED;
;         }
;         if constexpr (ALIGN_EPI) { if (wr == 0) PG8_BAR; }
	s_barrier
	s_add_i32 s88, s88, 2
	s_add_u32 s48, s48, 0x10000
	s_addc_u32 s49, s49, 0
	s_add_u32 s86, s86, 0x10000
	s_addc_u32 s87, s87, 0
	s_cmp_gt_u32 s88, 29
	s_cbranch_scc0 .LBB0_385
	s_and_b64 vcc, exec, s[34:35]
	s_cbranch_vccz .LBB0_388
	s_barrier

; #define PG8_STAGE(bufoff, gbase, voff) do { _Pragma("unroll") for (int _i = 0; _i < 2; ++_i) \
;         __builtin_amdgcn_global_load_lds((const unsigned*)((const char*)(gbase) + (voff)[_i]), (LAS unsigned*)(lds + (bufoff) + ldsw + _i * 8192), 16, 0, 0); } while (0)
; #define PG8_LDA(dst, b, h) do { _Pragma("unroll") for (int m = 0; m < 4; ++m) _Pragma("unroll") for (int k = 0; k < 2; ++k) dst[m][k] = *(const LAS bf16x8*)(lds + PG8_SA(b, h) + aoff + m * 2048 + k * 1024); } while (0)
; #define PG8_LDB(dst, b, h) do { _Pragma("unroll") for (int n = 0; n < 2; ++n) _Pragma("unroll") for (int k = 0; k < 2; ++k) dst[n][k] = *(const LAS bf16x8*)(lds + PG8_SB(b, h) + boff + n * 2048 + k * 1024); } while (0)
; #define PG8_MMA(ai, bj, At, Bt) do { __builtin_amdgcn_s_setprio(1); _Pragma("unroll") for (int m = 0; m < 4; ++m) _Pragma("unroll") for (int n = 0; n < 2; ++n) _Pragma("unroll") for (int k = 0; k < 2; ++k) \
;         acc[ai][bj][m][n] = __builtin_amdgcn_mfma_f32_16x16x32_bf16(Bt[n][k], At[m][k], acc[ai][bj][m][n], 0, 0, 0); __builtin_amdgcn_s_setprio(0); } while (0)
; #define PG8_WAIT_V(n) asm volatile("s_waitcnt vmcnt(" #n ")" ::: "memory")
; #define PG8_WAIT_L(n) asm volatile("s_waitcnt lgkmcnt(" #n ")" ::: "memory")
; #define PG8_BAR __builtin_amdgcn_s_barrier()
; #define PG8_SCHED __builtin_amdgcn_sched_barrier(0)
; template <class Epi, bool ALIGN_EPI>
; __device__ __forceinline__ void gemm_phase(LAS unsigned char* lds, const Gemm g, const StaticOrder& S, const Epi& E, const int tid) {
;     ...
;         for (int t = 0; t < nt; t += 2) {
;             const bool last = (t == nt - 2);
;             const char* a1 = cA + (size_t)(t + 1) * kstepA;
;             const char* a2 = last ? nA : cA + (size_t)(t + 2) * kstepA; const char* b2 = last ? nB : cB + (size_t)(t + 2) * kstepB;
;             const char* a3 = a2 + kstepA; const char* b3 = b2 + kstepB;
;             PG8_LDB(B0, 0, 0); PG8_LDB(B1, 0, 1); PG8_SCHED; PG8_LDA(At, 0, 0); PG8_STAGE(PG8_SA(1, 1), a1 + hstepA, voffA);
;             PG8_WAIT_V(8); PG8_WAIT_L(0); PG8_BAR; PG8_MMA(0, 0, At, B0); PG8_MMA(0, 1, At, B1); PG8_BAR; PG8_SCHED;
.LBB0_847:
	s_add_u32 s22, s10, 0xfff80080
	s_addc_u32 s23, s11, -1
	s_add_i32 s87, 0, 0x10000
	s_cmp_eq_u32 s86, 28
	s_cselect_b32 s35, s49, s23
	s_cselect_b32 s34, s82, s22
	v_add_u32_e32 v0, s87, v154
	s_cselect_b32 s23, s47, s85
	s_cselect_b32 s22, s83, s84
	s_add_i32 s90, 0, 0x14000
	s_waitcnt lgkmcnt(0)
	ds_read_b128 v[132:135], v0
	ds_read_b128 v[148:151], v0 offset:1024
	ds_read_b128 v[156:159], v0 offset:2048
	ds_read_b128 v[160:163], v0 offset:3072
	v_add_u32_e32 v0, s90, v154
	ds_read_b128 v[164:167], v0
	ds_read_b128 v[168:171], v0 offset:1024
	ds_read_b128 v[172:175], v0 offset:2048
	ds_read_b128 v[176:179], v0 offset:3072
	s_add_i32 m0, s70, 0xc000
	ds_read_b128 v[180:183], v155
	ds_read_b128 v[184:187], v155 offset:1024
	ds_read_b128 v[188:191], v155 offset:2048
	ds_read_b128 v[192:195], v155 offset:3072
	ds_read_b128 v[196:199], v155 offset:4096
	ds_read_b128 v[214:217], v155 offset:5120
	ds_read_b128 v[218:221], v155 offset:6144
	ds_read_b128 v[222:225], v155 offset:7168
	global_load_lds_dwordx4 v144, s[10:11]
	s_add_i32 m0, s70, 0xe000
	s_nop 0
	global_load_lds_dwordx4 v146, s[10:11]
	s_waitcnt vmcnt(8) lgkmcnt(0)
	s_barrier


; #define PG8_MMA(ai, bj, At, Bt) do { __builtin_amdgcn_s_setprio(1); _Pragma("unroll") for (int m = 0; m < 4; ++m) _Pragma("unroll") for (int n = 0; n < 2; ++n) _Pragma("unroll") for (int k = 0; k < 2; ++k) \
;         acc[ai][bj][m][n] = __builtin_amdgcn_mfma_f32_16x16x32_bf16(Bt[n][k], At[m][k], acc[ai][bj][m][n], 0, 0, 0); __builtin_amdgcn_s_setprio(0); } while (0)
; #define PG8_WAIT_V(n) asm volatile("s_waitcnt vmcnt(" #n ")" ::: "memory")
; #define PG8_WAIT_L(n) asm volatile("s_waitcnt lgkmcnt(" #n ")" ::: "memory")
; #define PG8_BAR __builtin_amdgcn_s_barrier()
; #define PG8_SCHED __builtin_amdgcn_sched_barrier(0)
; template <class Epi, bool ALIGN_EPI>
; __device__ __forceinline__ void gemm_phase(LAS unsigned char* lds, const Gemm g, const StaticOrder& S, const Epi& E, const int tid) {
;     ...
;             PG8_WAIT_V(8); PG8_WAIT_L(0); PG8_BAR; PG8_MMA(0, 0, At, B0); PG8_MMA(0, 1, At, B1); PG8_BAR; PG8_SCHED;
	v_mfma_f32_16x16x32_bf16 v[8:11], v[132:135], v[180:183], v[8:11]
	v_mfma_f32_16x16x32_bf16 v[56:59], v[156:159], v[180:183], v[56:59]
	v_mfma_f32_16x16x32_bf16 v[52:55], v[132:135], v[188:191], v[52:55]
	v_mfma_f32_16x16x32_bf16 v[48:51], v[156:159], v[188:191], v[48:51]
	v_mfma_f32_16x16x32_bf16 v[44:47], v[132:135], v[196:199], v[44:47]
	v_mfma_f32_16x16x32_bf16 v[40:43], v[156:159], v[196:199], v[40:43]
	v_mfma_f32_16x16x32_bf16 v[36:39], v[132:135], v[218:221], v[36:39]
	v_mfma_f32_16x16x32_bf16 v[32:35], v[156:159], v[218:221], v[32:35]
	v_mfma_f32_16x16x32_bf16 v[8:11], v[148:151], v[184:187], v[8:11]
	v_mfma_f32_16x16x32_bf16 v[56:59], v[160:163], v[184:187], v[56:59]
	v_mfma_f32_16x16x32_bf16 v[52:55], v[148:151], v[192:195], v[52:55]
	v_mfma_f32_16x16x32_bf16 v[48:51], v[160:163], v[192:195], v[48:51]
	v_mfma_f32_16x16x32_bf16 v[44:47], v[148:151], v[214:217], v[44:47]
	v_mfma_f32_16x16x32_bf16 v[40:43], v[160:163], v[214:217], v[40:43]
	v_mfma_f32_16x16x32_bf16 v[36:39], v[148:151], v[222:225], v[36:39]
	v_mfma_f32_16x16x32_bf16 v[32:35], v[160:163], v[222:225], v[32:35]


; #define PG8_MMA(ai, bj, At, Bt) do { __builtin_amdgcn_s_setprio(1); _Pragma("unroll") for (int m = 0; m < 4; ++m) _Pragma("unroll") for (int n = 0; n < 2; ++n) _Pragma("unroll") for (int k = 0; k < 2; ++k) \
;         acc[ai][bj][m][n] = __builtin_amdgcn_mfma_f32_16x16x32_bf16(Bt[n][k], At[m][k], acc[ai][bj][m][n], 0, 0, 0); __builtin_amdgcn_s_setprio(0); } while (0)
; #define PG8_WAIT_V(n) asm volatile("s_waitcnt vmcnt(" #n ")" ::: "memory")
; #define PG8_WAIT_L(n) asm volatile("s_waitcnt lgkmcnt(" #n ")" ::: "memory")
; #define PG8_BAR __builtin_amdgcn_s_barrier()
; #define PG8_SCHED __builtin_amdgcn_sched_barrier(0)
; template <class Epi, bool ALIGN_EPI>
; __device__ __forceinline__ void gemm_phase(LAS unsigned char* lds, const Gemm g, const StaticOrder& S, const Epi& E, const int tid) {
;     ...
;             PG8_WAIT_V(8); PG8_WAIT_L(0); PG8_BAR; PG8_MMA(0, 0, At, B0); PG8_MMA(0, 1, At, B1); PG8_BAR; PG8_SCHED;
	v_mfma_f32_16x16x32_bf16 v[2:5], v[164:167], v[180:183], v[4:7]
	v_mfma_f32_16x16x32_bf16 v[28:31], v[172:175], v[180:183], v[28:31]
	v_mfma_f32_16x16x32_bf16 v[96:99], v[164:167], v[188:191], v[96:99]
	v_mfma_f32_16x16x32_bf16 v[92:95], v[172:175], v[188:191], v[92:95]
	v_mfma_f32_16x16x32_bf16 v[88:91], v[164:167], v[196:199], v[88:91]
	v_mfma_f32_16x16x32_bf16 v[84:87], v[172:175], v[196:199], v[84:87]
	v_mfma_f32_16x16x32_bf16 v[80:83], v[164:167], v[218:221], v[80:83]
	v_mfma_f32_16x16x32_bf16 v[76:79], v[172:175], v[218:221], v[76:79]
	v_mfma_f32_16x16x32_bf16 v[2:5], v[168:171], v[184:187], v[2:5]
	v_mfma_f32_16x16x32_bf16 v[28:31], v[176:179], v[184:187], v[28:31]
	v_mfma_f32_16x16x32_bf16 v[96:99], v[168:171], v[192:195], v[96:99]
	v_mfma_f32_16x16x32_bf16 v[92:95], v[176:179], v[192:195], v[92:95]
	v_mfma_f32_16x16x32_bf16 v[88:91], v[168:171], v[214:217], v[88:91]
	v_mfma_f32_16x16x32_bf16 v[84:87], v[176:179], v[214:217], v[84:87]
	v_mfma_f32_16x16x32_bf16 v[80:83], v[168:171], v[222:225], v[80:83]
	v_mfma_f32_16x16x32_bf16 v[76:79], v[176:179], v[222:225], v[76:79]

; #define PG8_STAGE(bufoff, gbase, voff) do { _Pragma("unroll") for (int _i = 0; _i < 2; ++_i) \
;         __builtin_amdgcn_global_load_lds((const unsigned*)((const char*)(gbase) + (voff)[_i]), (LAS unsigned*)(lds + (bufoff) + ldsw + _i * 8192), 16, 0, 0); } while (0)
; #define PG8_LDA(dst, b, h) do { _Pragma("unroll") for (int m = 0; m < 4; ++m) _Pragma("unroll") for (int k = 0; k < 2; ++k) dst[m][k] = *(const LAS bf16x8*)(lds + PG8_SA(b, h) + aoff + m * 2048 + k * 1024); } while (0)
; #define PG8_MMA(ai, bj, At, Bt) do { __builtin_amdgcn_s_setprio(1); _Pragma("unroll") for (int m = 0; m < 4; ++m) _Pragma("unroll") for (int n = 0; n < 2; ++n) _Pragma("unroll") for (int k = 0; k < 2; ++k) \
;         acc[ai][bj][m][n] = __builtin_amdgcn_mfma_f32_16x16x32_bf16(Bt[n][k], At[m][k], acc[ai][bj][m][n], 0, 0, 0); __builtin_amdgcn_s_setprio(0); } while (0)
; #define PG8_WAIT_V(n) asm volatile("s_waitcnt vmcnt(" #n ")" ::: "memory")
; #define PG8_WAIT_L(n) asm volatile("s_waitcnt lgkmcnt(" #n ")" ::: "memory")
; #define PG8_BAR __builtin_amdgcn_s_barrier()
; #define PG8_SCHED __builtin_amdgcn_sched_barrier(0)
; template <class Epi, bool ALIGN_EPI>
; __device__ __forceinline__ void gemm_phase(LAS unsigned char* lds, const Gemm g, const StaticOrder& S, const Epi& E, const int tid) {
;     ...
;             PG8_WAIT_V(8); PG8_WAIT_L(0); PG8_BAR; PG8_MMA(0, 0, At, B0); PG8_MMA(0, 1, At, B1); PG8_BAR; PG8_SCHED;
;             PG8_LDA(At, 0, 1); PG8_STAGE(PG8_SB(0, 0), b2, voffB); PG8_STAGE(PG8_SB(0, 1), b2 + hstepB, voffB); PG8_STAGE(PG8_SA(0, 0), a2, voffA);
;             PG8_WAIT_V(8); PG8_WAIT_L(0); PG8_BAR; PG8_MMA(1, 0, At, B0); PG8_MMA(1, 1, At, B1); PG8_BAR; PG8_SCHED;
	s_barrier
	s_add_i32 s87, s87, s61
	s_mov_b32 m0, s87
	ds_read_b128 v[180:183], v155 offset:16384
	ds_read_b128 v[184:187], v155 offset:17408
	ds_read_b128 v[188:191], v155 offset:18432
	ds_read_b128 v[192:195], v155 offset:19456
	ds_read_b128 v[196:199], v155 offset:20480
	ds_read_b128 v[214:217], v155 offset:21504
	ds_read_b128 v[218:221], v155 offset:22528
	ds_read_b128 v[222:225], v155 offset:23552
	global_load_lds_dwordx4 v140, s[22:23]
	s_add_i32 m0, s87, 0x2000
	s_add_u32 s88, s22, 0x4000
	s_addc_u32 s89, s23, 0
	s_add_i32 s87, s90, s61
	global_load_lds_dwordx4 v136, s[22:23]
	s_mov_b32 m0, s87
	v_lshl_add_u64 v[152:153], s[34:35], 0, v[142:143]
	global_load_lds_dwordx4 v140, s[88:89]
	s_add_i32 m0, s87, 0x2000
	v_lshl_add_u64 v[200:201], s[34:35], 0, v[138:139]
	global_load_lds_dwordx4 v136, s[88:89]
	s_mov_b32 m0, s70
	s_nop 0
	global_load_lds_dwordx4 v[152:153], off
	s_mov_b32 m0, s71
	s_nop 0
	global_load_lds_dwordx4 v[200:201], off
	s_waitcnt vmcnt(8) lgkmcnt(0)
	s_barrier


; #define PG8_MMA(ai, bj, At, Bt) do { __builtin_amdgcn_s_setprio(1); _Pragma("unroll") for (int m = 0; m < 4; ++m) _Pragma("unroll") for (int n = 0; n < 2; ++n) _Pragma("unroll") for (int k = 0; k < 2; ++k) \
;         acc[ai][bj][m][n] = __builtin_amdgcn_mfma_f32_16x16x32_bf16(Bt[n][k], At[m][k], acc[ai][bj][m][n], 0, 0, 0); __builtin_amdgcn_s_setprio(0); } while (0)
; #define PG8_WAIT_V(n) asm volatile("s_waitcnt vmcnt(" #n ")" ::: "memory")
; #define PG8_WAIT_L(n) asm volatile("s_waitcnt lgkmcnt(" #n ")" ::: "memory")
; #define PG8_BAR __builtin_amdgcn_s_barrier()
; #define PG8_SCHED __builtin_amdgcn_sched_barrier(0)
; template <class Epi, bool ALIGN_EPI>
; __device__ __forceinline__ void gemm_phase(LAS unsigned char* lds, const Gemm g, const StaticOrder& S, const Epi& E, const int tid) {
;     ...
;             PG8_WAIT_V(8); PG8_WAIT_L(0); PG8_BAR; PG8_MMA(1, 0, At, B0); PG8_MMA(1, 1, At, B1); PG8_BAR; PG8_SCHED;
	v_mfma_f32_16x16x32_bf16 v[24:27], v[132:135], v[180:183], v[24:27]
	v_mfma_f32_16x16x32_bf16 v[20:23], v[156:159], v[180:183], v[20:23]
	v_mfma_f32_16x16x32_bf16 v[64:67], v[132:135], v[188:191], v[64:67]
	v_mfma_f32_16x16x32_bf16 v[72:75], v[156:159], v[188:191], v[72:75]
	v_mfma_f32_16x16x32_bf16 v[16:19], v[132:135], v[196:199], v[16:19]
	v_mfma_f32_16x16x32_bf16 v[12:15], v[156:159], v[196:199], v[12:15]
	v_mfma_f32_16x16x32_bf16 v[60:63], v[132:135], v[218:221], v[60:63]
	v_mfma_f32_16x16x32_bf16 v[68:71], v[156:159], v[218:221], v[68:71]
	v_mfma_f32_16x16x32_bf16 v[24:27], v[148:151], v[184:187], v[24:27]
	v_mfma_f32_16x16x32_bf16 v[20:23], v[160:163], v[184:187], v[20:23]
	v_mfma_f32_16x16x32_bf16 v[64:67], v[148:151], v[192:195], v[64:67]
	v_mfma_f32_16x16x32_bf16 v[72:75], v[160:163], v[192:195], v[72:75]
	v_mfma_f32_16x16x32_bf16 v[16:19], v[148:151], v[214:217], v[16:19]
	v_mfma_f32_16x16x32_bf16 v[12:15], v[160:163], v[214:217], v[12:15]
	v_mfma_f32_16x16x32_bf16 v[60:63], v[148:151], v[222:225], v[60:63]
	v_mfma_f32_16x16x32_bf16 v[68:71], v[160:163], v[222:225], v[68:71]


; #define PG8_MMA(ai, bj, At, Bt) do { __builtin_amdgcn_s_setprio(1); _Pragma("unroll") for (int m = 0; m < 4; ++m) _Pragma("unroll") for (int n = 0; n < 2; ++n) _Pragma("unroll") for (int k = 0; k < 2; ++k) \
;         acc[ai][bj][m][n] = __builtin_amdgcn_mfma_f32_16x16x32_bf16(Bt[n][k], At[m][k], acc[ai][bj][m][n], 0, 0, 0); __builtin_amdgcn_s_setprio(0); } while (0)
; #define PG8_WAIT_V(n) asm volatile("s_waitcnt vmcnt(" #n ")" ::: "memory")
; #define PG8_WAIT_L(n) asm volatile("s_waitcnt lgkmcnt(" #n ")" ::: "memory")
; #define PG8_BAR __builtin_amdgcn_s_barrier()
; #define PG8_SCHED __builtin_amdgcn_sched_barrier(0)
; template <class Epi, bool ALIGN_EPI>
; __device__ __forceinline__ void gemm_phase(LAS unsigned char* lds, const Gemm g, const StaticOrder& S, const Epi& E, const int tid) {
;     ...
;             PG8_WAIT_V(8); PG8_WAIT_L(0); PG8_BAR; PG8_MMA(1, 0, At, B0); PG8_MMA(1, 1, At, B1); PG8_BAR; PG8_SCHED;
	v_mfma_f32_16x16x32_bf16 v[128:131], v[164:167], v[180:183], v[128:131]
	v_mfma_f32_16x16x32_bf16 v[124:127], v[172:175], v[180:183], v[124:127]
	v_mfma_f32_16x16x32_bf16 v[120:123], v[164:167], v[188:191], v[120:123]
	v_mfma_f32_16x16x32_bf16 v[116:119], v[172:175], v[188:191], v[116:119]
	v_mfma_f32_16x16x32_bf16 v[112:115], v[164:167], v[196:199], v[112:115]
	v_mfma_f32_16x16x32_bf16 v[108:111], v[172:175], v[196:199], v[108:111]
	v_mfma_f32_16x16x32_bf16 v[104:107], v[164:167], v[218:221], v[104:107]
	v_mfma_f32_16x16x32_bf16 v[100:103], v[172:175], v[218:221], v[100:103]
	v_mfma_f32_16x16x32_bf16 v[128:131], v[168:171], v[184:187], v[128:131]
	v_mfma_f32_16x16x32_bf16 v[124:127], v[176:179], v[184:187], v[124:127]
	v_mfma_f32_16x16x32_bf16 v[120:123], v[168:171], v[192:195], v[120:123]
	v_mfma_f32_16x16x32_bf16 v[116:119], v[176:179], v[192:195], v[116:119]
	v_mfma_f32_16x16x32_bf16 v[112:115], v[168:171], v[214:217], v[112:115]
	v_mfma_f32_16x16x32_bf16 v[108:111], v[176:179], v[214:217], v[108:111]
	v_mfma_f32_16x16x32_bf16 v[104:107], v[168:171], v[222:225], v[104:107]
	v_mfma_f32_16x16x32_bf16 v[100:103], v[176:179], v[222:225], v[100:103]

; #define PG8_STAGE(bufoff, gbase, voff) do { _Pragma("unroll") for (int _i = 0; _i < 2; ++_i) \
;         __builtin_amdgcn_global_load_lds((const unsigned*)((const char*)(gbase) + (voff)[_i]), (LAS unsigned*)(lds + (bufoff) + ldsw + _i * 8192), 16, 0, 0); } while (0)
; #define PG8_LDA(dst, b, h) do { _Pragma("unroll") for (int m = 0; m < 4; ++m) _Pragma("unroll") for (int k = 0; k < 2; ++k) dst[m][k] = *(const LAS bf16x8*)(lds + PG8_SA(b, h) + aoff + m * 2048 + k * 1024); } while (0)
; #define PG8_LDB(dst, b, h) do { _Pragma("unroll") for (int n = 0; n < 2; ++n) _Pragma("unroll") for (int k = 0; k < 2; ++k) dst[n][k] = *(const LAS bf16x8*)(lds + PG8_SB(b, h) + boff + n * 2048 + k * 1024); } while (0)
; #define PG8_MMA(ai, bj, At, Bt) do { __builtin_amdgcn_s_setprio(1); _Pragma("unroll") for (int m = 0; m < 4; ++m) _Pragma("unroll") for (int n = 0; n < 2; ++n) _Pragma("unroll") for (int k = 0; k < 2; ++k) \
;         acc[ai][bj][m][n] = __builtin_amdgcn_mfma_f32_16x16x32_bf16(Bt[n][k], At[m][k], acc[ai][bj][m][n], 0, 0, 0); __builtin_amdgcn_s_setprio(0); } while (0)
; #define PG8_WAIT_V(n) asm volatile("s_waitcnt vmcnt(" #n ")" ::: "memory")
; #define PG8_WAIT_L(n) asm volatile("s_waitcnt lgkmcnt(" #n ")" ::: "memory")
; #define PG8_BAR __builtin_amdgcn_s_barrier()
; #define PG8_SCHED __builtin_amdgcn_sched_barrier(0)
; template <class Epi, bool ALIGN_EPI>
; __device__ __forceinline__ void gemm_phase(LAS unsigned char* lds, const Gemm g, const StaticOrder& S, const Epi& E, const int tid) {
;     ...
;             PG8_WAIT_V(8); PG8_WAIT_L(0); PG8_BAR; PG8_MMA(1, 0, At, B0); PG8_MMA(1, 1, At, B1); PG8_BAR; PG8_SCHED;
;             PG8_LDB(B0, 1, 0); PG8_LDB(B1, 1, 1); PG8_SCHED; PG8_LDA(At, 1, 0); PG8_STAGE(PG8_SA(0, 1), a2 + hstepA, voffA);
;             PG8_WAIT_V(8); PG8_WAIT_L(0); PG8_BAR; PG8_MMA(0, 0, At, B0); PG8_MMA(0, 1, At, B1); PG8_BAR; PG8_SCHED;
	s_barrier
	s_add_i32 s87, 0, 0x18000
	v_add_u32_e32 v0, s87, v154
	s_add_i32 s88, 0, 0x1c000
	ds_read_b128 v[132:135], v0
	ds_read_b128 v[148:151], v0 offset:1024
	ds_read_b128 v[156:159], v0 offset:2048
	ds_read_b128 v[160:163], v0 offset:3072
	v_add_u32_e32 v0, s88, v154
	ds_read_b128 v[164:167], v0
	ds_read_b128 v[168:171], v0 offset:1024
	ds_read_b128 v[172:175], v0 offset:2048
	ds_read_b128 v[176:179], v0 offset:3072
	s_add_u32 s34, s34, 0x80000
	s_addc_u32 s35, s35, 0
	s_mov_b32 m0, s72
	ds_read_b128 v[180:183], v155 offset:32768
	ds_read_b128 v[184:187], v155 offset:33792
	ds_read_b128 v[188:191], v155 offset:34816
	ds_read_b128 v[192:195], v155 offset:35840
	ds_read_b128 v[196:199], v155 offset:36864
	ds_read_b128 v[214:217], v155 offset:37888
	ds_read_b128 v[218:221], v155 offset:38912
	ds_read_b128 v[222:225], v155 offset:39936
	global_load_lds_dwordx4 v142, s[34:35]
	s_mov_b32 m0, s73
	s_nop 0
	global_load_lds_dwordx4 v138, s[34:35]
	s_waitcnt vmcnt(8) lgkmcnt(0)
	s_barrier


; #define PG8_MMA(ai, bj, At, Bt) do { __builtin_amdgcn_s_setprio(1); _Pragma("unroll") for (int m = 0; m < 4; ++m) _Pragma("unroll") for (int n = 0; n < 2; ++n) _Pragma("unroll") for (int k = 0; k < 2; ++k) \
;         acc[ai][bj][m][n] = __builtin_amdgcn_mfma_f32_16x16x32_bf16(Bt[n][k], At[m][k], acc[ai][bj][m][n], 0, 0, 0); __builtin_amdgcn_s_setprio(0); } while (0)
; #define PG8_WAIT_V(n) asm volatile("s_waitcnt vmcnt(" #n ")" ::: "memory")
; #define PG8_WAIT_L(n) asm volatile("s_waitcnt lgkmcnt(" #n ")" ::: "memory")
; #define PG8_BAR __builtin_amdgcn_s_barrier()
; #define PG8_SCHED __builtin_amdgcn_sched_barrier(0)
; template <class Epi, bool ALIGN_EPI>
; __device__ __forceinline__ void gemm_phase(LAS unsigned char* lds, const Gemm g, const StaticOrder& S, const Epi& E, const int tid) {
;     ...
;             PG8_WAIT_V(8); PG8_WAIT_L(0); PG8_BAR; PG8_MMA(0, 0, At, B0); PG8_MMA(0, 1, At, B1); PG8_BAR; PG8_SCHED;
	v_mfma_f32_16x16x32_bf16 v[6:9], v[132:135], v[180:183], v[8:11]
	v_mfma_f32_16x16x32_bf16 v[56:59], v[156:159], v[180:183], v[56:59]
	v_mfma_f32_16x16x32_bf16 v[52:55], v[132:135], v[188:191], v[52:55]
	v_mfma_f32_16x16x32_bf16 v[48:51], v[156:159], v[188:191], v[48:51]
	v_mfma_f32_16x16x32_bf16 v[44:47], v[132:135], v[196:199], v[44:47]
	v_mfma_f32_16x16x32_bf16 v[40:43], v[156:159], v[196:199], v[40:43]
	v_mfma_f32_16x16x32_bf16 v[36:39], v[132:135], v[218:221], v[36:39]
	v_mfma_f32_16x16x32_bf16 v[32:35], v[156:159], v[218:221], v[32:35]
	v_mfma_f32_16x16x32_bf16 v[8:11], v[148:151], v[184:187], v[6:9]
	v_mfma_f32_16x16x32_bf16 v[56:59], v[160:163], v[184:187], v[56:59]
	v_mfma_f32_16x16x32_bf16 v[52:55], v[148:151], v[192:195], v[52:55]
	v_mfma_f32_16x16x32_bf16 v[48:51], v[160:163], v[192:195], v[48:51]
	v_mfma_f32_16x16x32_bf16 v[44:47], v[148:151], v[214:217], v[44:47]
	v_mfma_f32_16x16x32_bf16 v[40:43], v[160:163], v[214:217], v[40:43]
	v_mfma_f32_16x16x32_bf16 v[36:39], v[148:151], v[222:225], v[36:39]
	v_mfma_f32_16x16x32_bf16 v[32:35], v[160:163], v[222:225], v[32:35]


; #define PG8_MMA(ai, bj, At, Bt) do { __builtin_amdgcn_s_setprio(1); _Pragma("unroll") for (int m = 0; m < 4; ++m) _Pragma("unroll") for (int n = 0; n < 2; ++n) _Pragma("unroll") for (int k = 0; k < 2; ++k) \
;         acc[ai][bj][m][n] = __builtin_amdgcn_mfma_f32_16x16x32_bf16(Bt[n][k], At[m][k], acc[ai][bj][m][n], 0, 0, 0); __builtin_amdgcn_s_setprio(0); } while (0)
; #define PG8_WAIT_V(n) asm volatile("s_waitcnt vmcnt(" #n ")" ::: "memory")
; #define PG8_WAIT_L(n) asm volatile("s_waitcnt lgkmcnt(" #n ")" ::: "memory")
; #define PG8_BAR __builtin_amdgcn_s_barrier()
; #define PG8_SCHED __builtin_amdgcn_sched_barrier(0)
; template <class Epi, bool ALIGN_EPI>
; __device__ __forceinline__ void gemm_phase(LAS unsigned char* lds, const Gemm g, const StaticOrder& S, const Epi& E, const int tid) {
;     ...
;             PG8_WAIT_V(8); PG8_WAIT_L(0); PG8_BAR; PG8_MMA(0, 0, At, B0); PG8_MMA(0, 1, At, B1); PG8_BAR; PG8_SCHED;
	v_mfma_f32_16x16x32_bf16 v[2:5], v[164:167], v[180:183], v[2:5]
	v_mfma_f32_16x16x32_bf16 v[28:31], v[172:175], v[180:183], v[28:31]
	v_mfma_f32_16x16x32_bf16 v[96:99], v[164:167], v[188:191], v[96:99]
	v_mfma_f32_16x16x32_bf16 v[92:95], v[172:175], v[188:191], v[92:95]
	v_mfma_f32_16x16x32_bf16 v[88:91], v[164:167], v[196:199], v[88:91]
	v_mfma_f32_16x16x32_bf16 v[84:87], v[172:175], v[196:199], v[84:87]
	v_mfma_f32_16x16x32_bf16 v[80:83], v[164:167], v[218:221], v[80:83]
	v_mfma_f32_16x16x32_bf16 v[76:79], v[172:175], v[218:221], v[76:79]
	v_mfma_f32_16x16x32_bf16 v[4:7], v[168:171], v[184:187], v[2:5]
	v_mfma_f32_16x16x32_bf16 v[28:31], v[176:179], v[184:187], v[28:31]
	v_mfma_f32_16x16x32_bf16 v[96:99], v[168:171], v[192:195], v[96:99]
	v_mfma_f32_16x16x32_bf16 v[92:95], v[176:179], v[192:195], v[92:95]
	v_mfma_f32_16x16x32_bf16 v[88:91], v[168:171], v[214:217], v[88:91]
	v_mfma_f32_16x16x32_bf16 v[84:87], v[176:179], v[214:217], v[84:87]
	v_mfma_f32_16x16x32_bf16 v[80:83], v[168:171], v[222:225], v[80:83]
	v_mfma_f32_16x16x32_bf16 v[76:79], v[176:179], v[222:225], v[76:79]

; #define PG8_STAGE(bufoff, gbase, voff) do { _Pragma("unroll") for (int _i = 0; _i < 2; ++_i) \
;         __builtin_amdgcn_global_load_lds((const unsigned*)((const char*)(gbase) + (voff)[_i]), (LAS unsigned*)(lds + (bufoff) + ldsw + _i * 8192), 16, 0, 0); } while (0)
; #define PG8_LDA(dst, b, h) do { _Pragma("unroll") for (int m = 0; m < 4; ++m) _Pragma("unroll") for (int k = 0; k < 2; ++k) dst[m][k] = *(const LAS bf16x8*)(lds + PG8_SA(b, h) + aoff + m * 2048 + k * 1024); } while (0)
; #define PG8_MMA(ai, bj, At, Bt) do { __builtin_amdgcn_s_setprio(1); _Pragma("unroll") for (int m = 0; m < 4; ++m) _Pragma("unroll") for (int n = 0; n < 2; ++n) _Pragma("unroll") for (int k = 0; k < 2; ++k) \
;         acc[ai][bj][m][n] = __builtin_amdgcn_mfma_f32_16x16x32_bf16(Bt[n][k], At[m][k], acc[ai][bj][m][n], 0, 0, 0); __builtin_amdgcn_s_setprio(0); } while (0)
; #define PG8_WAIT_V(n) asm volatile("s_waitcnt vmcnt(" #n ")" ::: "memory")
; #define PG8_WAIT_L(n) asm volatile("s_waitcnt lgkmcnt(" #n ")" ::: "memory")
; #define PG8_BAR __builtin_amdgcn_s_barrier()
; #define PG8_SCHED __builtin_amdgcn_sched_barrier(0)
; template <class Epi, bool ALIGN_EPI>
; __device__ __forceinline__ void gemm_phase(LAS unsigned char* lds, const Gemm g, const StaticOrder& S, const Epi& E, const int tid) {
;     ...
;             PG8_WAIT_V(8); PG8_WAIT_L(0); PG8_BAR; PG8_MMA(0, 0, At, B0); PG8_MMA(0, 1, At, B1); PG8_BAR; PG8_SCHED;
;             PG8_LDA(At, 1, 1); PG8_STAGE(PG8_SB(1, 0), b3, voffB); PG8_STAGE(PG8_SB(1, 1), b3 + hstepB, voffB); PG8_STAGE(PG8_SA(1, 0), a3, voffA);
;             PG8_WAIT_V(8); PG8_WAIT_L(0); PG8_BAR; PG8_MMA(1, 0, At, B0); PG8_MMA(1, 1, At, B1); PG8_BAR; PG8_SCHED;
	s_barrier
	s_add_u32 s34, s22, 0x8000
	s_addc_u32 s35, s23, 0
	s_add_i32 s87, s87, s61
	s_mov_b32 m0, s87
	ds_read_b128 v[180:183], v155 offset:49152
	ds_read_b128 v[184:187], v155 offset:50176
	ds_read_b128 v[188:191], v155 offset:51200
	ds_read_b128 v[192:195], v155 offset:52224
	ds_read_b128 v[196:199], v155 offset:53248
	ds_read_b128 v[214:217], v155 offset:54272
	ds_read_b128 v[218:221], v155 offset:55296
	ds_read_b128 v[222:225], v155 offset:56320
	global_load_lds_dwordx4 v140, s[34:35]
	s_add_i32 m0, s87, 0x2000
	s_add_u32 s22, s22, 0xc000
	s_addc_u32 s23, s23, 0
	global_load_lds_dwordx4 v136, s[34:35]
	s_add_i32 s34, s88, s61
	s_mov_b32 m0, s34
	s_nop 0
	global_load_lds_dwordx4 v140, s[22:23]
	s_add_i32 m0, s34, 0x2000
	s_nop 0
	global_load_lds_dwordx4 v136, s[22:23]
	v_lshl_add_u64 v[2:3], v[152:153], 0, s[6:7]
	s_mov_b32 m0, s78
	s_nop 0
	global_load_lds_dwordx4 v[2:3], off
	v_lshl_add_u64 v[2:3], v[200:201], 0, s[6:7]
	s_mov_b32 m0, s79
	s_nop 0
	global_load_lds_dwordx4 v[2:3], off
	s_waitcnt vmcnt(8) lgkmcnt(0)
	s_barrier


; #define PG8_MMA(ai, bj, At, Bt) do { __builtin_amdgcn_s_setprio(1); _Pragma("unroll") for (int m = 0; m < 4; ++m) _Pragma("unroll") for (int n = 0; n < 2; ++n) _Pragma("unroll") for (int k = 0; k < 2; ++k) \
;         acc[ai][bj][m][n] = __builtin_amdgcn_mfma_f32_16x16x32_bf16(Bt[n][k], At[m][k], acc[ai][bj][m][n], 0, 0, 0); __builtin_amdgcn_s_setprio(0); } while (0)
; #define PG8_WAIT_V(n) asm volatile("s_waitcnt vmcnt(" #n ")" ::: "memory")
; #define PG8_WAIT_L(n) asm volatile("s_waitcnt lgkmcnt(" #n ")" ::: "memory")
; #define PG8_BAR __builtin_amdgcn_s_barrier()
; #define PG8_SCHED __builtin_amdgcn_sched_barrier(0)
; template <class Epi, bool ALIGN_EPI>
; __device__ __forceinline__ void gemm_phase(LAS unsigned char* lds, const Gemm g, const StaticOrder& S, const Epi& E, const int tid) {
;     ...
;             PG8_WAIT_V(8); PG8_WAIT_L(0); PG8_BAR; PG8_MMA(1, 0, At, B0); PG8_MMA(1, 1, At, B1); PG8_BAR; PG8_SCHED;
	v_mfma_f32_16x16x32_bf16 v[24:27], v[132:135], v[180:183], v[24:27]
	v_mfma_f32_16x16x32_bf16 v[20:23], v[156:159], v[180:183], v[20:23]
	v_mfma_f32_16x16x32_bf16 v[64:67], v[132:135], v[188:191], v[64:67]
	v_mfma_f32_16x16x32_bf16 v[72:75], v[156:159], v[188:191], v[72:75]
	v_mfma_f32_16x16x32_bf16 v[16:19], v[132:135], v[196:199], v[16:19]
	v_mfma_f32_16x16x32_bf16 v[12:15], v[156:159], v[196:199], v[12:15]
	v_mfma_f32_16x16x32_bf16 v[60:63], v[132:135], v[218:221], v[60:63]
	v_mfma_f32_16x16x32_bf16 v[68:71], v[156:159], v[218:221], v[68:71]
	v_mfma_f32_16x16x32_bf16 v[24:27], v[148:151], v[184:187], v[24:27]
	v_mfma_f32_16x16x32_bf16 v[20:23], v[160:163], v[184:187], v[20:23]
	v_mfma_f32_16x16x32_bf16 v[64:67], v[148:151], v[192:195], v[64:67]
	v_mfma_f32_16x16x32_bf16 v[72:75], v[160:163], v[192:195], v[72:75]
	v_mfma_f32_16x16x32_bf16 v[16:19], v[148:151], v[214:217], v[16:19]
	v_mfma_f32_16x16x32_bf16 v[12:15], v[160:163], v[214:217], v[12:15]
	v_mfma_f32_16x16x32_bf16 v[60:63], v[148:151], v[222:225], v[60:63]
	v_mfma_f32_16x16x32_bf16 v[68:71], v[160:163], v[222:225], v[68:71]


; #define PG8_MMA(ai, bj, At, Bt) do { __builtin_amdgcn_s_setprio(1); _Pragma("unroll") for (int m = 0; m < 4; ++m) _Pragma("unroll") for (int n = 0; n < 2; ++n) _Pragma("unroll") for (int k = 0; k < 2; ++k) \
;         acc[ai][bj][m][n] = __builtin_amdgcn_mfma_f32_16x16x32_bf16(Bt[n][k], At[m][k], acc[ai][bj][m][n], 0, 0, 0); __builtin_amdgcn_s_setprio(0); } while (0)
; #define PG8_WAIT_V(n) asm volatile("s_waitcnt vmcnt(" #n ")" ::: "memory")
; #define PG8_WAIT_L(n) asm volatile("s_waitcnt lgkmcnt(" #n ")" ::: "memory")
; #define PG8_BAR __builtin_amdgcn_s_barrier()
; #define PG8_SCHED __builtin_amdgcn_sched_barrier(0)
; template <class Epi, bool ALIGN_EPI>
; __device__ __forceinline__ void gemm_phase(LAS unsigned char* lds, const Gemm g, const StaticOrder& S, const Epi& E, const int tid) {
;     ...
;             PG8_WAIT_V(8); PG8_WAIT_L(0); PG8_BAR; PG8_MMA(1, 0, At, B0); PG8_MMA(1, 1, At, B1); PG8_BAR; PG8_SCHED;
	v_mfma_f32_16x16x32_bf16 v[128:131], v[164:167], v[180:183], v[128:131]
	v_mfma_f32_16x16x32_bf16 v[124:127], v[172:175], v[180:183], v[124:127]
	v_mfma_f32_16x16x32_bf16 v[120:123], v[164:167], v[188:191], v[120:123]
	v_mfma_f32_16x16x32_bf16 v[116:119], v[172:175], v[188:191], v[116:119]
	v_mfma_f32_16x16x32_bf16 v[112:115], v[164:167], v[196:199], v[112:115]
	v_mfma_f32_16x16x32_bf16 v[108:111], v[172:175], v[196:199], v[108:111]
	v_mfma_f32_16x16x32_bf16 v[104:107], v[164:167], v[218:221], v[104:107]
	v_mfma_f32_16x16x32_bf16 v[100:103], v[172:175], v[218:221], v[100:103]
	v_mfma_f32_16x16x32_bf16 v[128:131], v[168:171], v[184:187], v[128:131]
	v_mfma_f32_16x16x32_bf16 v[124:127], v[176:179], v[184:187], v[124:127]
	v_mfma_f32_16x16x32_bf16 v[120:123], v[168:171], v[192:195], v[120:123]
	v_mfma_f32_16x16x32_bf16 v[116:119], v[176:179], v[192:195], v[116:119]
	v_mfma_f32_16x16x32_bf16 v[112:115], v[168:171], v[214:217], v[112:115]
	v_mfma_f32_16x16x32_bf16 v[108:111], v[176:179], v[214:217], v[108:111]
	v_mfma_f32_16x16x32_bf16 v[104:107], v[168:171], v[222:225], v[104:107]
	v_mfma_f32_16x16x32_bf16 v[100:103], v[176:179], v[222:225], v[100:103]

; #define PG8_MMA(ai, bj, At, Bt) do { __builtin_amdgcn_s_setprio(1); _Pragma("unroll") for (int m = 0; m < 4; ++m) _Pragma("unroll") for (int n = 0; n < 2; ++n) _Pragma("unroll") for (int k = 0; k < 2; ++k) \
;         acc[ai][bj][m][n] = __builtin_amdgcn_mfma_f32_16x16x32_bf16(Bt[n][k], At[m][k], acc[ai][bj][m][n], 0, 0, 0); __builtin_amdgcn_s_setprio(0); } while (0)
; #define PG8_WAIT_V(n) asm volatile("s_waitcnt vmcnt(" #n ")" ::: "memory")
; #define PG8_WAIT_L(n) asm volatile("s_waitcnt lgkmcnt(" #n ")" ::: "memory")
; #define PG8_BAR __builtin_amdgcn_s_barrier()
; #define PG8_SCHED __builtin_amdgcn_sched_barrier(0)
; template <class Epi, bool ALIGN_EPI>
; __device__ __forceinline__ void gemm_phase(LAS unsigned char* lds, const Gemm g, const StaticOrder& S, const Epi& E, const int tid) {
;     ...
;         for (int t = 0; t < nt; t += 2) {
;     ...
;             PG8_WAIT_V(8); PG8_WAIT_L(0); PG8_BAR; PG8_MMA(1, 0, At, B0); PG8_MMA(1, 1, At, B1); PG8_BAR; PG8_SCHED;
;         }
;         if constexpr (ALIGN_EPI) { if (wr == 0) PG8_BAR; }
	s_barrier
	s_add_i32 s86, s86, 2
	s_add_u32 s10, s10, 0x100
	s_addc_u32 s11, s11, 0
	s_add_u32 s84, s84, 0x10000
	s_addc_u32 s85, s85, 0
	s_cmp_gt_u32 s86, 29
	s_cbranch_scc0 .LBB0_847
	s_and_b64 vcc, exec, s[44:45]
	s_cbranch_vccz .LBB0_850
	s_barrier
